# x1 (G_OUT result) kept lane-linear in dead workspace: G_OUT stores and G_MLPOUT residual loads become coalesced 1KB bursts; MLPOUT still writes x2 to d_out in true layout
# speedup vs baseline: 1.0174x; 1.0092x over previous
; __device__ __forceinline__ unsigned cvt_pk_bf16(float lo, float hi) { unsigned r; asm volatile("s_nop 0\n\tv_cvt_pk_bf16_f32 %0, %1, %2" : "=v"(r) : "v"(lo), "v"(hi)); return r; }
; __device__ __forceinline__ f32x4 sig4(const f32x4 v) { return (f32x4){sigmoidf_(v[0]), sigmoidf_(v[1]), sigmoidf_(v[2]), sigmoidf_(v[3])}; }
;     __device__ __forceinline__ void operator()(const typename AccT<I8>::type (&acc)[2][2][4][2], const Unit& u, int wr, int wc, int fr, int fq) const {
;         const int row0 = u.pm * BM + wr * 64 + fr, col0 = u.pn * BM + wc * 32 + 4 * fq;
;         f32x4 sv[2][2];
;         if (I8) {
; #pragma unroll
;             for (int bj = 0; bj < 2; ++bj)
; #pragma unroll
;                 for (int n = 0; n < 2; ++n) sv[bj][n] = *(const f32x4*)(swc + col0 + bj * HALF + n * 16);
;         }
;         float rsv[8];
; #pragma unroll
;         for (int s = 0; s < 8; ++s) { const int r = row0 + (s >> 2) * HALF + (s & 3) * 16; float rs = 1.f; if (MODE == 1) rs = __builtin_amdgcn_rsqf(rstd[r] * (1.0f / 4096.0f) + 1e-6f); if (I8) rs *= sxr[r]; rsv[s] = rs; }
;         RowIn cur, nxt;
;         load_row(cur, (size_t)row0 * 4096 + col0);
; #pragma unroll
;         for (int s = 0; s < 8; ++s) { const int ai = s >> 2, m = s & 3; const int r = row0 + ai * HALF + m * 16; const size_t off = (size_t)r * 4096 + col0;
;                 if (s + 1 < 8) load_row(nxt, (size_t)(row0 + ((s + 1) >> 2) * HALF + ((s + 1) & 3) * 16) * 4096 + col0);
;                 const float rs = rsv[s];
;                 float ss = 0.f, mx = 0.f;
; #pragma unroll
;                 for (int bj = 0; bj < 2; ++bj)
; #pragma unroll
;                     for (int n = 0; n < 2; ++n) { const size_t o = off + bj * HALF + n * 16; const f32x4 b = cur.b[bj][n]; f32x4 v;
;                         if constexpr (I8) v = __builtin_convertvector(acc[ai][bj][m][n], f32x4) * rs * sv[bj][n]; else v = acc[ai][bj][m][n];
;                         if (MODE == 1) { const u32x2 pw = cur.pw[bj][n]; const f32x4 pp = (f32x4){bf_lo(pw.x), bf_hi(pw.x), bf_lo(pw.y), bf_hi(pw.y)}; v = sig4(I8 ? v : v * rs) * pp; }
;                         const f32x4 x = b + v; *(f32x4*)(out + o) = x;
;                         if (MODE == 0 && XB) { u32x2 w; w.x = cvt_pk_bf16(x[0], x[1]); w.y = cvt_pk_bf16(x[2], x[3]); *(u32x2*)(XB + o) = w; ss += (x[0] * x[0] + x[1] * x[1]) + (x[2] * x[2] + x[3] * x[3]);
.LBB0_1724:
	s_lshl_b32 s98, s6, 4
	s_add_i32 s98, s98, s2
	s_sub_i32 s99, s98, 888
	s_cmp_lt_u32 s98, 888
	s_cselect_b32 s98, s98, s99
	s_mov_b32 s99, 0x4200000
	s_cselect_b32 s99, 0x3f600000, s99
	s_lshl_b32 s98, s98, 18
	s_add_u32 s98, s98, s99
	v_and_b32_e32 v250, 63, v0
	v_lshlrev_b32_e32 v250, 4, v250
	v_lshrrev_b32_e32 v251, 6, v0
	v_lshl_add_u32 v250, v251, 15, v250
	v_add_u32_e32 v250, s98, v250
	v_mov_b32_e32 v251, 0
	v_lshl_add_u64 v[250:251], s[96:97], 0, v[250:251]
	v_mov_b32_e32 v148, v0
	v_cvt_f32_i32_e32 v145, v145
	v_ashrrev_i32_e32 v34, 2, v148
	v_and_b32_e32 v34, 0xffffffc0, v34
	v_lshl_add_u32 v149, s6, 8, v34
	v_lshrrev_b32_e32 v34, 1, v148
	v_and_b32_e32 v34, 0x60, v34
	v_bfe_u32 v187, v148, 4, 2
	v_lshl_or_b32 v34, s2, 8, v34
	v_lshl_or_b32 v190, v187, 2, v34
	v_ashrrev_i32_e32 v191, 31, v190
	v_and_or_b32 v206, v148, 15, v149
	v_lshlrev_b64 v[146:147], 2, v[190:191]
	v_ashrrev_i32_e32 v207, 31, v206
	v_or_b32_e32 v214, 16, v206
	v_or_b32_e32 v210, 32, v206
	v_or_b32_e32 v204, 48, v206
	v_add_u32_e32 v198, 0x90, v206
	v_add_u32_e32 v194, 0xa0, v206
	v_add_u32_e32 v188, 0xb0, v206
	v_lshl_add_u64 v[34:35], s[14:15], 0, v[146:147]
	v_lshl_add_u64 v[148:149], v[206:207], 2, s[16:17]
	v_ashrrev_i32_e32 v215, 31, v214
	v_ashrrev_i32_e32 v211, 31, v210
	v_ashrrev_i32_e32 v205, 31, v204
	v_ashrrev_i32_e32 v199, 31, v198
	v_ashrrev_i32_e32 v195, 31, v194
	v_ashrrev_i32_e32 v189, 31, v188
	global_load_dwordx4 v[62:65], v[34:35], off
	global_load_dwordx4 v[42:45], v[34:35], off offset:64
	global_load_dwordx4 v[38:41], v[34:35], off offset:512
	s_nop 0
	global_load_dwordx4 v[34:37], v[34:35], off offset:576
	v_lshl_add_u64 v[150:151], v[214:215], 2, s[16:17]
	v_lshl_add_u64 v[152:153], v[210:211], 2, s[16:17]
	v_lshl_add_u64 v[154:155], v[204:205], 2, s[16:17]
	v_lshl_add_u64 v[156:157], v[198:199], 2, s[16:17]
	v_lshl_add_u64 v[158:159], v[194:195], 2, s[16:17]
	v_lshl_add_u64 v[160:161], v[188:189], 2, s[16:17]
	global_load_dword v216, v[148:149], off
	global_load_dword v212, v[150:151], off
	global_load_dword v208, v[152:153], off
	global_load_dword v202, v[154:155], off
	global_load_dword v196, v[156:157], off
	global_load_dword v192, v[158:159], off
	global_load_dword v186, v[160:161], off
	global_load_dword v200, v[148:149], off offset:512
	v_lshlrev_b64 v[148:149], 14, v[206:207]
	v_lshl_add_u64 v[148:149], s[64:65], 0, v[148:149]
	v_lshl_add_u64 v[148:149], v[148:149], 0, v[146:147]
	global_load_dwordx4 v[238:241], v[148:149], off
	global_load_dwordx4 v[170:173], v[148:149], off offset:64
	global_load_dwordx4 v[166:169], v[148:149], off offset:512
	global_load_dwordx4 v[162:165], v[148:149], off offset:576
	v_lshlrev_b64 v[148:149], 14, v[214:215]
	v_lshl_add_u64 v[148:149], s[64:65], 0, v[148:149]
	v_lshl_add_u64 v[146:147], v[148:149], 0, v[146:147]
	global_load_dwordx4 v[158:161], v[146:147], off
	global_load_dwordx4 v[154:157], v[146:147], off offset:64
	global_load_dwordx4 v[150:153], v[146:147], off offset:512
	s_nop 0
	global_load_dwordx4 v[146:149], v[146:147], off offset:576
	v_cvt_f32_i32_e32 v144, v144
	v_cvt_f32_i32_e32 v143, v143
	v_cvt_f32_i32_e32 v142, v142
	v_cvt_f32_i32_e32 v229, v139
	v_cvt_f32_i32_e32 v228, v138
	v_cvt_f32_i32_e32 v231, v141
	v_cvt_f32_i32_e32 v230, v140
	v_cvt_f32_i32_e32 v225, v135
	v_cvt_f32_i32_e32 v224, v134
	v_cvt_f32_i32_e32 v227, v137
	v_cvt_f32_i32_e32 v226, v136
	v_cvt_f32_i32_e32 v219, v131
	v_cvt_f32_i32_e32 v218, v130
	v_cvt_f32_i32_e32 v223, v133
	v_cvt_f32_i32_e32 v222, v132
	v_lshlrev_b64 v[130:131], 12, v[206:207]
	v_readlane_b32 s68, v254, 8
	v_cndmask_b32_e64 v193, 0, 1, s[22:23]
	v_lshl_add_u64 v[134:135], v[130:131], 0, v[190:191]
	v_readlane_b32 s74, v254, 14
	v_readlane_b32 s75, v254, 15
	v_cmp_ne_u32_e64 s[8:9], 1, v193
	v_cmp_eq_u32_e64 s[6:7], 0, v187
	s_mov_b64 s[98:99], 0x0
	v_lshl_add_u64 v[220:221], v[250:251], 0, s[98:99]
	s_andn2_b64 vcc, exec, s[22:23]
	v_readlane_b32 s69, v254, 9
	v_readlane_b32 s70, v254, 10
	v_readlane_b32 s71, v254, 11
	v_readlane_b32 s72, v254, 12
	v_readlane_b32 s73, v254, 13
	s_waitcnt vmcnt(0)
	v_mov_b32_e32 v217, v216
	v_pk_mul_f32 v[130:131], v[216:217], v[142:143] op_sel_hi:[0,1]
	v_pk_mul_f32 v[132:133], v[216:217], v[144:145] op_sel_hi:[0,1]
	v_pk_fma_f32 v[132:133], v[64:65], v[132:133], v[240:241]
	v_pk_fma_f32 v[130:131], v[62:63], v[130:131], v[238:239]
	global_store_dwordx4 v[220:221], v[130:133], off
	s_cbranch_vccnz .LBB0_1783
; __device__ __forceinline__ unsigned cvt_pk_bf16(float lo, float hi) { unsigned r; asm volatile("s_nop 0\n\tv_cvt_pk_bf16_f32 %0, %1, %2" : "=v"(r) : "v"(lo), "v"(hi)); return r; }
; __device__ __forceinline__ f32x4 sig4(const f32x4 v) { return (f32x4){sigmoidf_(v[0]), sigmoidf_(v[1]), sigmoidf_(v[2]), sigmoidf_(v[3])}; }
;     __device__ __forceinline__ void operator()(const typename AccT<I8>::type (&acc)[2][2][4][2], const Unit& u, int wr, int wc, int fr, int fq) const {
;     ...
;                     for (int n = 0; n < 2; ++n) { const size_t o = off + bj * HALF + n * 16; const f32x4 b = cur.b[bj][n]; f32x4 v;
;                         if constexpr (I8) v = __builtin_convertvector(acc[ai][bj][m][n], f32x4) * rs * sv[bj][n]; else v = acc[ai][bj][m][n];
;                         if (MODE == 1) { const u32x2 pw = cur.pw[bj][n]; const f32x4 pp = (f32x4){bf_lo(pw.x), bf_hi(pw.x), bf_lo(pw.y), bf_hi(pw.y)}; v = sig4(I8 ? v : v * rs) * pp; }
;                         const f32x4 x = b + v; *(f32x4*)(out + o) = x;
;                         if (MODE == 0 && XB) { u32x2 w; w.x = cvt_pk_bf16(x[0], x[1]); w.y = cvt_pk_bf16(x[2], x[3]); *(u32x2*)(XB + o) = w; ss += (x[0] * x[0] + x[1] * x[1]) + (x[2] * x[2] + x[3] * x[3]);
;                             if (RM) mx = fmaxf(fmaxf(mx, fmaxf(fabsf(x[0]), fabsf(x[1]))), fmaxf(fabsf(x[2]), fabsf(x[3]))); } }
;                 if (MODE == 0 && XB) { ss += __shfl_xor(ss, 16); ss += __shfl_xor(ss, 32); if (fq == 0) unsafeAtomicAdd(SS + r, ss);
;                     if (RM) { mx = fmaxf(mx, __shfl_xor(mx, 16)); mx = fmaxf(mx, __shfl_xor(mx, 32)); if (fq == 0) atomicMax(RM + r, __builtin_bit_cast(unsigned, mx)); } }
	v_readlane_b32 s2, v254, 40
	v_lshlrev_b64 v[238:239], 1, v[134:135]
	v_readlane_b32 s3, v254, 41
	s_nop 0
	v_cvt_pk_bf16_f32 v136, v130, v131
	s_nop 0
	v_cvt_pk_bf16_f32 v137, v132, v133
	v_mov_b32_e32 v142, v216
	v_mov_b32_e32 v143, v216
	v_lshl_add_u64 v[134:135], s[2:3], 0, v[238:239]
	global_store_dwordx2 v[134:135], v[136:137], off
	v_mul_f32_e32 v134, v131, v131
	v_mul_f32_e32 v135, v133, v133
	v_fmac_f32_e32 v134, v130, v130
	v_fmac_f32_e32 v135, v132, v132
	v_add_f32_e32 v144, v134, v135
	v_pk_mul_f32 v[134:135], v[142:143], v[230:231]
	v_pk_mul_f32 v[138:139], v[216:217], v[228:229]
	v_pk_fma_f32 v[136:137], v[44:45], v[134:135], v[172:173]
	v_pk_fma_f32 v[134:135], v[42:43], v[138:139], v[170:171]
	v_or_b32_e32 v140, 32, v238
	v_mov_b32_e32 v141, v239
	global_store_dwordx4 v[220:221], v[134:137], off offset:1024
	s_nop 0
	v_cvt_pk_bf16_f32 v138, v134, v135
	s_nop 0
	v_cvt_pk_bf16_f32 v139, v136, v137
	v_lshl_add_u64 v[140:141], s[2:3], 0, v[140:141]
	global_store_dwordx2 v[140:141], v[138:139], off
	v_mul_f32_e32 v138, v135, v135
	v_mul_f32_e32 v139, v137, v137
	v_fmac_f32_e32 v138, v134, v134
	v_fmac_f32_e32 v139, v136, v136
	v_add_f32_e32 v138, v138, v139
	v_add_f32_e32 v187, v144, v138
	v_pk_mul_f32 v[138:139], v[142:143], v[226:227]
	v_pk_mul_f32 v[144:145], v[216:217], v[224:225]
	v_pk_fma_f32 v[140:141], v[40:41], v[138:139], v[168:169]
	v_pk_fma_f32 v[138:139], v[38:39], v[144:145], v[166:167]
	v_mul_f32_e32 v145, v141, v141
	v_mul_f32_e32 v144, v139, v139
	v_fmac_f32_e32 v144, v138, v138
	v_fmac_f32_e32 v145, v140, v140
	v_add_f32_e32 v144, v144, v145
	v_pk_mul_f32 v[142:143], v[142:143], v[222:223]
	v_pk_mul_f32 v[244:245], v[216:217], v[218:219]
	v_add_f32_e32 v187, v187, v144
	v_pk_fma_f32 v[144:145], v[36:37], v[142:143], v[164:165]
	v_pk_fma_f32 v[142:143], v[34:35], v[244:245], v[162:163]
	v_mul_f32_e32 v197, v145, v145
	v_mul_f32_e32 v193, v143, v143
	v_fmac_f32_e32 v193, v142, v142
	v_fmac_f32_e32 v197, v144, v144
	v_add_f32_e32 v193, v193, v197
	v_and_b32_e32 v197, 64, v236
	v_add_f32_e32 v193, v187, v193
	v_xor_b32_e32 v187, 16, v236
	v_add_u32_e32 v201, 64, v197
	v_cmp_lt_i32_e32 vcc, v187, v201
	v_or_b32_e32 v242, 0x100, v238
	v_mov_b32_e32 v243, v239
	v_cndmask_b32_e32 v187, v236, v187, vcc
	v_lshlrev_b32_e32 v187, 2, v187
	ds_bpermute_b32 v197, v187, v193
	v_or_b32_e32 v238, 0x120, v238
	global_store_dwordx4 v[220:221], v[138:141], off offset:2048
	s_nop 0
	v_cvt_pk_bf16_f32 v240, v138, v139
	s_nop 0
	v_cvt_pk_bf16_f32 v241, v140, v141
	s_waitcnt lgkmcnt(0)
	v_add_f32_e32 v197, v193, v197
	v_xor_b32_e32 v193, 32, v236
	v_cmp_lt_i32_e32 vcc, v193, v201
	v_lshl_add_u64 v[242:243], s[2:3], 0, v[242:243]
	v_lshl_add_u64 v[238:239], s[2:3], 0, v[238:239]
	v_cndmask_b32_e32 v193, v236, v193, vcc
	v_lshlrev_b32_e32 v193, 2, v193
	ds_bpermute_b32 v201, v193, v197
	global_store_dwordx2 v[242:243], v[240:241], off
	global_store_dwordx4 v[220:221], v[142:145], off offset:3072
	s_nop 0
	v_cvt_pk_bf16_f32 v240, v142, v143
	s_nop 0
	v_cvt_pk_bf16_f32 v241, v144, v145
	global_store_dwordx2 v[238:239], v[240:241], off
	s_and_saveexec_b64 s[2:3], s[6:7]
	s_cbranch_execz .LBB0_1727
	v_lshl_add_u64 v[238:239], v[206:207], 2, s[10:11]
	s_waitcnt lgkmcnt(0)
	v_add_f32_e32 v197, v197, v201
	global_atomic_add_f32 v[238:239], v197, off

; __device__ __forceinline__ unsigned cvt_pk_bf16(float lo, float hi) { unsigned r; asm volatile("s_nop 0\n\tv_cvt_pk_bf16_f32 %0, %1, %2" : "=v"(r) : "v"(lo), "v"(hi)); return r; }
; __device__ __forceinline__ f32x4 sig4(const f32x4 v) { return (f32x4){sigmoidf_(v[0]), sigmoidf_(v[1]), sigmoidf_(v[2]), sigmoidf_(v[3])}; }
;     __device__ __forceinline__ void operator()(const typename AccT<I8>::type (&acc)[2][2][4][2], const Unit& u, int wr, int wc, int fr, int fq) const {
;     ...
;         for (int s = 0; s < 8; ++s) { const int ai = s >> 2, m = s & 3; const int r = row0 + ai * HALF + m * 16; const size_t off = (size_t)r * 4096 + col0;
;                 if (s + 1 < 8) load_row(nxt, (size_t)(row0 + ((s + 1) >> 2) * HALF + ((s + 1) & 3) * 16) * 4096 + col0);
;                 const float rs = rsv[s];
;                 float ss = 0.f, mx = 0.f;
; #pragma unroll
;                 for (int bj = 0; bj < 2; ++bj)
; #pragma unroll
;                     for (int n = 0; n < 2; ++n) { const size_t o = off + bj * HALF + n * 16; const f32x4 b = cur.b[bj][n]; f32x4 v;
;                         if constexpr (I8) v = __builtin_convertvector(acc[ai][bj][m][n], f32x4) * rs * sv[bj][n]; else v = acc[ai][bj][m][n];
;                         if (MODE == 1) { const u32x2 pw = cur.pw[bj][n]; const f32x4 pp = (f32x4){bf_lo(pw.x), bf_hi(pw.x), bf_lo(pw.y), bf_hi(pw.y)}; v = sig4(I8 ? v : v * rs) * pp; }
;                         const f32x4 x = b + v; *(f32x4*)(out + o) = x;
;                         if (MODE == 0 && XB) { u32x2 w; w.x = cvt_pk_bf16(x[0], x[1]); w.y = cvt_pk_bf16(x[2], x[3]); *(u32x2*)(XB + o) = w; ss += (x[0] * x[0] + x[1] * x[1]) + (x[2] * x[2] + x[3] * x[3]);
;                             if (RM) mx = fmaxf(fmaxf(mx, fmaxf(fabsf(x[0]), fabsf(x[1]))), fmaxf(fabsf(x[2]), fabsf(x[3]))); } }
;                 if (MODE == 0 && XB) { ss += __shfl_xor(ss, 16); ss += __shfl_xor(ss, 32); if (fq == 0) unsafeAtomicAdd(SS + r, ss);
;                     if (RM) { mx = fmaxf(mx, __shfl_xor(mx, 16)); mx = fmaxf(mx, __shfl_xor(mx, 32)); if (fq == 0) atomicMax(RM + r, __builtin_bit_cast(unsigned, mx)); } }
.LBB0_1730:
	v_mov_b32_e32 v134, v216
	v_mov_b32_e32 v135, v216
	s_waitcnt lgkmcnt(0)
	v_pk_mul_f32 v[130:131], v[134:135], v[230:231]
	v_pk_mul_f32 v[136:137], v[216:217], v[228:229]
	v_pk_fma_f32 v[132:133], v[44:45], v[130:131], v[172:173]
	v_pk_fma_f32 v[130:131], v[42:43], v[136:137], v[170:171]
	global_store_dwordx4 v[220:221], v[130:133], off offset:1024
	v_pk_mul_f32 v[136:137], v[216:217], v[224:225]
	s_nop 0
	v_pk_mul_f32 v[130:131], v[134:135], v[226:227]
	s_nop 0
	v_pk_fma_f32 v[132:133], v[40:41], v[130:131], v[168:169]
	v_pk_fma_f32 v[130:131], v[38:39], v[136:137], v[166:167]
	global_store_dwordx4 v[220:221], v[130:133], off offset:2048
	s_nop 1
	v_pk_mul_f32 v[130:131], v[134:135], v[222:223]
	v_pk_mul_f32 v[134:135], v[216:217], v[218:219]
	v_pk_fma_f32 v[132:133], v[36:37], v[130:131], v[164:165]
	v_pk_fma_f32 v[130:131], v[34:35], v[134:135], v[162:163]
	global_store_dwordx4 v[220:221], v[130:133], off offset:3072
.LBB0_1731:
	s_waitcnt lgkmcnt(0)
	s_nop 0
	v_lshlrev_b64 v[130:131], 14, v[210:211]
	v_lshl_add_u64 v[130:131], s[64:65], 0, v[130:131]
	v_lshl_add_u64 v[130:131], v[190:191], 2, v[130:131]
	global_load_dwordx4 v[142:145], v[130:131], off
	global_load_dwordx4 v[138:141], v[130:131], off offset:64
	global_load_dwordx4 v[134:137], v[130:131], off offset:512
	s_nop 0
	global_load_dwordx4 v[130:133], v[130:131], off offset:576
	v_cvt_f32_i32_e32 v127, v127
	v_cvt_f32_i32_e32 v126, v126
	v_cvt_f32_i32_e32 v129, v129
	v_cvt_f32_i32_e32 v128, v128
	v_mov_b32_e32 v213, v212
	v_lshlrev_b64 v[162:163], 12, v[214:215]
	v_pk_mul_f32 v[126:127], v[212:213], v[126:127] op_sel_hi:[0,1]
	v_lshl_add_u64 v[172:173], v[162:163], 0, v[190:191]
	v_pk_fma_f32 v[126:127], v[62:63], v[126:127], v[158:159]
	v_cvt_f32_i32_e32 v169, v123
	v_cvt_f32_i32_e32 v168, v122
	v_cvt_f32_i32_e32 v171, v125
	v_cvt_f32_i32_e32 v170, v124
	v_cvt_f32_i32_e32 v165, v119
	v_cvt_f32_i32_e32 v164, v118
	v_cvt_f32_i32_e32 v167, v121
	v_cvt_f32_i32_e32 v166, v120
	v_cvt_f32_i32_e32 v159, v115
	v_cvt_f32_i32_e32 v158, v114
	v_cvt_f32_i32_e32 v163, v117
	v_cvt_f32_i32_e32 v162, v116
	v_readlane_b32 s68, v254, 8
	v_pk_mul_f32 v[128:129], v[212:213], v[128:129] op_sel_hi:[0,1]
	v_readlane_b32 s74, v254, 14
	v_readlane_b32 s75, v254, 15
	v_pk_fma_f32 v[128:129], v[64:65], v[128:129], v[160:161]
	s_and_b64 vcc, exec, s[8:9]
	s_mov_b64 s[98:99], 0x1000
	v_lshl_add_u64 v[160:161], v[250:251], 0, s[98:99]
	v_readlane_b32 s69, v254, 9
	v_readlane_b32 s70, v254, 10
	v_readlane_b32 s71, v254, 11
	v_readlane_b32 s72, v254, 12
	v_readlane_b32 s73, v254, 13
	global_store_dwordx4 v[160:161], v[126:129], off
	s_cbranch_vccnz .LBB0_1784
	v_readlane_b32 s2, v254, 40
	v_lshlrev_b64 v[216:217], 1, v[172:173]
	v_readlane_b32 s3, v254, 41
	s_nop 0
	v_cvt_pk_bf16_f32 v114, v126, v127
	s_nop 0
	v_cvt_pk_bf16_f32 v115, v128, v129
	v_mov_b32_e32 v122, v212
	v_mov_b32_e32 v123, v212
	v_lshl_add_u64 v[116:117], s[2:3], 0, v[216:217]
	global_store_dwordx2 v[116:117], v[114:115], off
	v_mul_f32_e32 v114, v127, v127
	v_mul_f32_e32 v115, v129, v129
	v_fmac_f32_e32 v114, v126, v126
	v_fmac_f32_e32 v115, v128, v128
	v_add_f32_e32 v124, v114, v115
	v_pk_mul_f32 v[114:115], v[122:123], v[170:171]
	v_pk_mul_f32 v[118:119], v[212:213], v[168:169]
	v_pk_fma_f32 v[116:117], v[44:45], v[114:115], v[156:157]
	v_pk_fma_f32 v[114:115], v[42:43], v[118:119], v[154:155]
	v_or_b32_e32 v120, 32, v216
	v_mov_b32_e32 v121, v217
	global_store_dwordx4 v[160:161], v[114:117], off offset:1024
	s_nop 0
	v_cvt_pk_bf16_f32 v118, v114, v115
	s_nop 0
	v_cvt_pk_bf16_f32 v119, v116, v117
	v_lshl_add_u64 v[120:121], s[2:3], 0, v[120:121]
	global_store_dwordx2 v[120:121], v[118:119], off
	v_mul_f32_e32 v118, v115, v115
	v_mul_f32_e32 v119, v117, v117
	v_fmac_f32_e32 v118, v114, v114
	v_fmac_f32_e32 v119, v116, v116
	v_add_f32_e32 v118, v118, v119
	v_add_f32_e32 v172, v124, v118
	v_pk_mul_f32 v[118:119], v[122:123], v[166:167]
	v_pk_mul_f32 v[124:125], v[212:213], v[164:165]
	v_pk_fma_f32 v[120:121], v[40:41], v[118:119], v[152:153]
	v_pk_fma_f32 v[118:119], v[38:39], v[124:125], v[150:151]
	v_mul_f32_e32 v125, v121, v121
	v_mul_f32_e32 v124, v119, v119
	v_fmac_f32_e32 v124, v118, v118
	v_fmac_f32_e32 v125, v120, v120
	v_add_f32_e32 v124, v124, v125
	v_add_f32_e32 v187, v172, v124
	v_pk_mul_f32 v[122:123], v[122:123], v[162:163]
	v_pk_mul_f32 v[172:173], v[212:213], v[158:159]
	v_pk_fma_f32 v[124:125], v[36:37], v[122:123], v[148:149]
	v_pk_fma_f32 v[122:123], v[34:35], v[172:173], v[146:147]
	v_mul_f32_e32 v173, v125, v125
	v_mul_f32_e32 v172, v123, v123
	v_fmac_f32_e32 v172, v122, v122
	v_fmac_f32_e32 v173, v124, v124
	v_add_f32_e32 v172, v172, v173
	v_add_f32_e32 v173, v187, v172
	v_and_b32_e32 v187, 64, v236
	v_xor_b32_e32 v172, 16, v236
	v_add_u32_e32 v193, 64, v187
	v_cmp_lt_i32_e32 vcc, v172, v193
	v_or_b32_e32 v220, 0x100, v216
	v_mov_b32_e32 v221, v217
	v_cndmask_b32_e32 v172, v236, v172, vcc
	v_lshlrev_b32_e32 v172, 2, v172
	ds_bpermute_b32 v187, v172, v173
	v_or_b32_e32 v216, 0x120, v216
	global_store_dwordx4 v[160:161], v[118:121], off offset:2048
	s_nop 0
	v_cvt_pk_bf16_f32 v218, v118, v119
	s_nop 0
	v_cvt_pk_bf16_f32 v219, v120, v121
	s_waitcnt lgkmcnt(0)
	v_add_f32_e32 v187, v173, v187
	v_xor_b32_e32 v173, 32, v236
	v_cmp_lt_i32_e32 vcc, v173, v193
	v_lshl_add_u64 v[220:221], s[2:3], 0, v[220:221]
	v_lshl_add_u64 v[216:217], s[2:3], 0, v[216:217]
	v_cndmask_b32_e32 v173, v236, v173, vcc
	v_lshlrev_b32_e32 v173, 2, v173
	ds_bpermute_b32 v193, v173, v187
	global_store_dwordx2 v[220:221], v[218:219], off
	global_store_dwordx4 v[160:161], v[122:125], off offset:3072
	s_nop 0
	v_cvt_pk_bf16_f32 v218, v122, v123
	s_nop 0
	v_cvt_pk_bf16_f32 v219, v124, v125
	global_store_dwordx2 v[216:217], v[218:219], off
	s_and_saveexec_b64 s[2:3], s[6:7]
	s_cbranch_execz .LBB0_1734
	v_lshl_add_u64 v[216:217], v[214:215], 2, s[10:11]
	s_waitcnt lgkmcnt(0)
	v_add_f32_e32 v187, v187, v193
	global_atomic_add_f32 v[216:217], v187, off

; __device__ __forceinline__ unsigned cvt_pk_bf16(float lo, float hi) { unsigned r; asm volatile("s_nop 0\n\tv_cvt_pk_bf16_f32 %0, %1, %2" : "=v"(r) : "v"(lo), "v"(hi)); return r; }
; __device__ __forceinline__ f32x4 sig4(const f32x4 v) { return (f32x4){sigmoidf_(v[0]), sigmoidf_(v[1]), sigmoidf_(v[2]), sigmoidf_(v[3])}; }
;     __device__ __forceinline__ void operator()(const typename AccT<I8>::type (&acc)[2][2][4][2], const Unit& u, int wr, int wc, int fr, int fq) const {
;     ...
;         for (int s = 0; s < 8; ++s) { const int ai = s >> 2, m = s & 3; const int r = row0 + ai * HALF + m * 16; const size_t off = (size_t)r * 4096 + col0;
;                 if (s + 1 < 8) load_row(nxt, (size_t)(row0 + ((s + 1) >> 2) * HALF + ((s + 1) & 3) * 16) * 4096 + col0);
;                 const float rs = rsv[s];
;                 float ss = 0.f, mx = 0.f;
; #pragma unroll
;                 for (int bj = 0; bj < 2; ++bj)
; #pragma unroll
;                     for (int n = 0; n < 2; ++n) { const size_t o = off + bj * HALF + n * 16; const f32x4 b = cur.b[bj][n]; f32x4 v;
;                         if constexpr (I8) v = __builtin_convertvector(acc[ai][bj][m][n], f32x4) * rs * sv[bj][n]; else v = acc[ai][bj][m][n];
;                         if (MODE == 1) { const u32x2 pw = cur.pw[bj][n]; const f32x4 pp = (f32x4){bf_lo(pw.x), bf_hi(pw.x), bf_lo(pw.y), bf_hi(pw.y)}; v = sig4(I8 ? v : v * rs) * pp; }
;                         const f32x4 x = b + v; *(f32x4*)(out + o) = x;
;                         if (MODE == 0 && XB) { u32x2 w; w.x = cvt_pk_bf16(x[0], x[1]); w.y = cvt_pk_bf16(x[2], x[3]); *(u32x2*)(XB + o) = w; ss += (x[0] * x[0] + x[1] * x[1]) + (x[2] * x[2] + x[3] * x[3]);
;                             if (RM) mx = fmaxf(fmaxf(mx, fmaxf(fabsf(x[0]), fabsf(x[1]))), fmaxf(fabsf(x[2]), fabsf(x[3]))); } }
;                 if (MODE == 0 && XB) { ss += __shfl_xor(ss, 16); ss += __shfl_xor(ss, 32); if (fq == 0) unsafeAtomicAdd(SS + r, ss);
;                     if (RM) { mx = fmaxf(mx, __shfl_xor(mx, 16)); mx = fmaxf(mx, __shfl_xor(mx, 32)); if (fq == 0) atomicMax(RM + r, __builtin_bit_cast(unsigned, mx)); } }
.LBB0_1737:
	v_mov_b32_e32 v118, v212
	v_mov_b32_e32 v119, v212
	s_waitcnt lgkmcnt(0)
	v_pk_mul_f32 v[114:115], v[118:119], v[170:171]
	v_pk_mul_f32 v[120:121], v[212:213], v[168:169]
	v_pk_fma_f32 v[116:117], v[44:45], v[114:115], v[156:157]
	v_pk_fma_f32 v[114:115], v[42:43], v[120:121], v[154:155]
	global_store_dwordx4 v[160:161], v[114:117], off offset:1024
	v_pk_mul_f32 v[120:121], v[212:213], v[164:165]
	s_nop 0
	v_pk_mul_f32 v[114:115], v[118:119], v[166:167]
	s_nop 0
	v_pk_fma_f32 v[116:117], v[40:41], v[114:115], v[152:153]
	v_pk_fma_f32 v[114:115], v[38:39], v[120:121], v[150:151]
	global_store_dwordx4 v[160:161], v[114:117], off offset:2048
	s_nop 1
	v_pk_mul_f32 v[114:115], v[118:119], v[162:163]
	v_pk_mul_f32 v[118:119], v[212:213], v[158:159]
	v_pk_fma_f32 v[116:117], v[36:37], v[114:115], v[148:149]
	v_pk_fma_f32 v[114:115], v[34:35], v[118:119], v[146:147]
	global_store_dwordx4 v[160:161], v[114:117], off offset:3072
.LBB0_1738:
	s_waitcnt lgkmcnt(0)
	s_nop 0
	v_lshlrev_b64 v[114:115], 14, v[204:205]
	v_lshl_add_u64 v[114:115], s[64:65], 0, v[114:115]
	v_lshl_add_u64 v[114:115], v[190:191], 2, v[114:115]
	global_load_dwordx4 v[126:129], v[114:115], off
	global_load_dwordx4 v[122:125], v[114:115], off offset:64
	global_load_dwordx4 v[118:121], v[114:115], off offset:512
	s_nop 0
	global_load_dwordx4 v[114:117], v[114:115], off offset:576
	v_cvt_f32_i32_e32 v111, v111
	v_cvt_f32_i32_e32 v110, v110
	v_cvt_f32_i32_e32 v113, v113
	v_cvt_f32_i32_e32 v112, v112
	v_mov_b32_e32 v209, v208
	v_lshlrev_b64 v[146:147], 12, v[210:211]
	v_pk_mul_f32 v[110:111], v[208:209], v[110:111] op_sel_hi:[0,1]
	v_lshl_add_u64 v[156:157], v[146:147], 0, v[190:191]
	s_waitcnt vmcnt(8)
	v_pk_fma_f32 v[110:111], v[62:63], v[110:111], v[142:143]
	v_cvt_f32_i32_e32 v153, v107
	v_cvt_f32_i32_e32 v152, v106
	v_cvt_f32_i32_e32 v155, v109
	v_cvt_f32_i32_e32 v154, v108
	v_cvt_f32_i32_e32 v149, v103
	v_cvt_f32_i32_e32 v148, v102
	v_cvt_f32_i32_e32 v151, v105
	v_cvt_f32_i32_e32 v150, v104
	v_cvt_f32_i32_e32 v143, v99
	v_cvt_f32_i32_e32 v142, v98
	v_cvt_f32_i32_e32 v147, v101
	v_cvt_f32_i32_e32 v146, v100
	v_readlane_b32 s68, v254, 8
	v_pk_mul_f32 v[112:113], v[208:209], v[112:113] op_sel_hi:[0,1]
	v_readlane_b32 s74, v254, 14
	v_readlane_b32 s75, v254, 15
	v_pk_fma_f32 v[112:113], v[64:65], v[112:113], v[144:145]
	s_and_b64 vcc, exec, s[8:9]
	s_mov_b64 s[98:99], 0x2000
	v_lshl_add_u64 v[144:145], v[250:251], 0, s[98:99]
	v_readlane_b32 s69, v254, 9
	v_readlane_b32 s70, v254, 10
	v_readlane_b32 s71, v254, 11
	v_readlane_b32 s72, v254, 12
	v_readlane_b32 s73, v254, 13
	global_store_dwordx4 v[144:145], v[110:113], off
	s_cbranch_vccnz .LBB0_1785
	v_readlane_b32 s2, v254, 40
	v_lshlrev_b64 v[160:161], 1, v[156:157]
	v_readlane_b32 s3, v254, 41
	s_nop 0
	v_cvt_pk_bf16_f32 v98, v110, v111
	s_nop 0
	v_cvt_pk_bf16_f32 v99, v112, v113
	v_mov_b32_e32 v106, v208
	v_mov_b32_e32 v107, v208
	v_lshl_add_u64 v[100:101], s[2:3], 0, v[160:161]
	global_store_dwordx2 v[100:101], v[98:99], off
	v_mul_f32_e32 v98, v111, v111
	v_mul_f32_e32 v99, v113, v113
	v_fmac_f32_e32 v98, v110, v110
	v_fmac_f32_e32 v99, v112, v112
	v_add_f32_e32 v108, v98, v99
	v_pk_mul_f32 v[98:99], v[106:107], v[154:155]
	v_pk_mul_f32 v[102:103], v[208:209], v[152:153]
	s_waitcnt vmcnt(9)
	v_pk_fma_f32 v[100:101], v[44:45], v[98:99], v[140:141]
	v_pk_fma_f32 v[98:99], v[42:43], v[102:103], v[138:139]
	v_or_b32_e32 v104, 32, v160
	v_mov_b32_e32 v105, v161
	global_store_dwordx4 v[144:145], v[98:101], off offset:1024
	s_nop 0
	v_cvt_pk_bf16_f32 v102, v98, v99
	s_nop 0
	v_cvt_pk_bf16_f32 v103, v100, v101
	v_lshl_add_u64 v[104:105], s[2:3], 0, v[104:105]
	global_store_dwordx2 v[104:105], v[102:103], off
	v_mul_f32_e32 v102, v99, v99
	v_mul_f32_e32 v103, v101, v101
	v_fmac_f32_e32 v102, v98, v98
	v_fmac_f32_e32 v103, v100, v100
	v_add_f32_e32 v102, v102, v103
	v_add_f32_e32 v156, v108, v102
	v_pk_mul_f32 v[102:103], v[106:107], v[150:151]
	v_pk_mul_f32 v[108:109], v[208:209], v[148:149]
	s_waitcnt vmcnt(10)
	v_pk_fma_f32 v[104:105], v[40:41], v[102:103], v[136:137]
	v_pk_fma_f32 v[102:103], v[38:39], v[108:109], v[134:135]
	v_mul_f32_e32 v109, v105, v105
	v_mul_f32_e32 v108, v103, v103
	v_fmac_f32_e32 v108, v102, v102
	v_fmac_f32_e32 v109, v104, v104
	v_add_f32_e32 v108, v108, v109
	v_add_f32_e32 v164, v156, v108
	v_pk_mul_f32 v[106:107], v[106:107], v[146:147]
	v_pk_mul_f32 v[156:157], v[208:209], v[142:143]
	s_waitcnt vmcnt(9)
	v_pk_fma_f32 v[108:109], v[36:37], v[106:107], v[132:133]
	v_pk_fma_f32 v[106:107], v[34:35], v[156:157], v[130:131]
	v_mul_f32_e32 v157, v109, v109
	v_mul_f32_e32 v156, v107, v107
	v_fmac_f32_e32 v156, v106, v106
	v_fmac_f32_e32 v157, v108, v108
	v_add_f32_e32 v156, v156, v157
	v_add_f32_e32 v157, v164, v156
	v_and_b32_e32 v164, 64, v236
	v_xor_b32_e32 v156, 16, v236
	v_add_u32_e32 v164, 64, v164
	v_cmp_lt_i32_e32 vcc, v156, v164
	v_or_b32_e32 v162, 0x100, v160
	v_mov_b32_e32 v163, v161
	v_cndmask_b32_e32 v156, v236, v156, vcc
	v_lshlrev_b32_e32 v156, 2, v156
	ds_bpermute_b32 v165, v156, v157
	global_store_dwordx4 v[144:145], v[102:105], off offset:2048
	s_nop 0
	v_cvt_pk_bf16_f32 v158, v102, v103
	s_nop 0
	v_cvt_pk_bf16_f32 v159, v104, v105
	v_lshl_add_u64 v[162:163], s[2:3], 0, v[162:163]
	global_store_dwordx2 v[162:163], v[158:159], off
	global_store_dwordx4 v[144:145], v[106:109], off offset:3072
	s_waitcnt lgkmcnt(0)
	v_add_f32_e32 v158, v157, v165
	v_xor_b32_e32 v157, 32, v236
	v_cmp_lt_i32_e32 vcc, v157, v164
	v_or_b32_e32 v160, 0x120, v160
	v_lshl_add_u64 v[160:161], s[2:3], 0, v[160:161]
	v_cndmask_b32_e32 v157, v236, v157, vcc
	v_lshlrev_b32_e32 v157, 2, v157
	ds_bpermute_b32 v159, v157, v158
	s_nop 0
	v_cvt_pk_bf16_f32 v162, v106, v107
	s_nop 0
	v_cvt_pk_bf16_f32 v163, v108, v109
	global_store_dwordx2 v[160:161], v[162:163], off
	s_and_saveexec_b64 s[2:3], s[6:7]
	s_cbranch_execz .LBB0_1741
	v_lshl_add_u64 v[160:161], v[210:211], 2, s[10:11]
	s_waitcnt lgkmcnt(0)
	v_add_f32_e32 v158, v158, v159
	global_atomic_add_f32 v[160:161], v158, off

; __device__ __forceinline__ unsigned cvt_pk_bf16(float lo, float hi) { unsigned r; asm volatile("s_nop 0\n\tv_cvt_pk_bf16_f32 %0, %1, %2" : "=v"(r) : "v"(lo), "v"(hi)); return r; }
; __device__ __forceinline__ f32x4 sig4(const f32x4 v) { return (f32x4){sigmoidf_(v[0]), sigmoidf_(v[1]), sigmoidf_(v[2]), sigmoidf_(v[3])}; }
;     __device__ __forceinline__ void operator()(const typename AccT<I8>::type (&acc)[2][2][4][2], const Unit& u, int wr, int wc, int fr, int fq) const {
;     ...
;         for (int s = 0; s < 8; ++s) { const int ai = s >> 2, m = s & 3; const int r = row0 + ai * HALF + m * 16; const size_t off = (size_t)r * 4096 + col0;
;                 if (s + 1 < 8) load_row(nxt, (size_t)(row0 + ((s + 1) >> 2) * HALF + ((s + 1) & 3) * 16) * 4096 + col0);
;                 const float rs = rsv[s];
;                 float ss = 0.f, mx = 0.f;
; #pragma unroll
;                 for (int bj = 0; bj < 2; ++bj)
; #pragma unroll
;                     for (int n = 0; n < 2; ++n) { const size_t o = off + bj * HALF + n * 16; const f32x4 b = cur.b[bj][n]; f32x4 v;
;                         if constexpr (I8) v = __builtin_convertvector(acc[ai][bj][m][n], f32x4) * rs * sv[bj][n]; else v = acc[ai][bj][m][n];
;                         if (MODE == 1) { const u32x2 pw = cur.pw[bj][n]; const f32x4 pp = (f32x4){bf_lo(pw.x), bf_hi(pw.x), bf_lo(pw.y), bf_hi(pw.y)}; v = sig4(I8 ? v : v * rs) * pp; }
;                         const f32x4 x = b + v; *(f32x4*)(out + o) = x;
;                         if (MODE == 0 && XB) { u32x2 w; w.x = cvt_pk_bf16(x[0], x[1]); w.y = cvt_pk_bf16(x[2], x[3]); *(u32x2*)(XB + o) = w; ss += (x[0] * x[0] + x[1] * x[1]) + (x[2] * x[2] + x[3] * x[3]);
;                             if (RM) mx = fmaxf(fmaxf(mx, fmaxf(fabsf(x[0]), fabsf(x[1]))), fmaxf(fabsf(x[2]), fabsf(x[3]))); } }
;                 if (MODE == 0 && XB) { ss += __shfl_xor(ss, 16); ss += __shfl_xor(ss, 32); if (fq == 0) unsafeAtomicAdd(SS + r, ss);
;                     if (RM) { mx = fmaxf(mx, __shfl_xor(mx, 16)); mx = fmaxf(mx, __shfl_xor(mx, 32)); if (fq == 0) atomicMax(RM + r, __builtin_bit_cast(unsigned, mx)); } }
.LBB0_1744:
	v_mov_b32_e32 v102, v208
	v_mov_b32_e32 v103, v208
	s_waitcnt lgkmcnt(0)
	v_pk_mul_f32 v[98:99], v[102:103], v[154:155]
	v_pk_mul_f32 v[104:105], v[208:209], v[152:153]
	s_waitcnt vmcnt(8)
	v_pk_fma_f32 v[100:101], v[44:45], v[98:99], v[140:141]
	v_pk_fma_f32 v[98:99], v[42:43], v[104:105], v[138:139]
	global_store_dwordx4 v[144:145], v[98:101], off offset:1024
	v_pk_mul_f32 v[104:105], v[208:209], v[148:149]
	s_nop 0
	v_pk_mul_f32 v[98:99], v[102:103], v[150:151]
	s_waitcnt vmcnt(8)
	v_pk_fma_f32 v[100:101], v[40:41], v[98:99], v[136:137]
	v_pk_fma_f32 v[98:99], v[38:39], v[104:105], v[134:135]
	global_store_dwordx4 v[144:145], v[98:101], off offset:2048
	s_nop 1
	v_pk_mul_f32 v[98:99], v[102:103], v[146:147]
	v_pk_mul_f32 v[102:103], v[208:209], v[142:143]
	s_waitcnt vmcnt(8)
	v_pk_fma_f32 v[100:101], v[36:37], v[98:99], v[132:133]
	v_pk_fma_f32 v[98:99], v[34:35], v[102:103], v[130:131]
	global_store_dwordx4 v[144:145], v[98:101], off offset:3072
.LBB0_1745:
	s_waitcnt vmcnt(6)
	v_add_u32_e32 v130, 0x80, v206
	v_ashrrev_i32_e32 v131, 31, v130
	s_waitcnt lgkmcnt(0)
	v_lshlrev_b64 v[98:99], 14, v[130:131]
	v_lshl_add_u64 v[98:99], s[64:65], 0, v[98:99]
	v_lshl_add_u64 v[98:99], v[190:191], 2, v[98:99]
	global_load_dwordx4 v[110:113], v[98:99], off
	global_load_dwordx4 v[106:109], v[98:99], off offset:64
	global_load_dwordx4 v[102:105], v[98:99], off offset:512
	s_nop 0
	global_load_dwordx4 v[98:101], v[98:99], off offset:576
	v_cvt_f32_i32_e32 v95, v95
	v_cvt_f32_i32_e32 v94, v94
	v_cvt_f32_i32_e32 v97, v97
	v_cvt_f32_i32_e32 v96, v96
	v_mov_b32_e32 v203, v202
	v_lshlrev_b64 v[132:133], 12, v[204:205]
	v_pk_mul_f32 v[94:95], v[202:203], v[94:95] op_sel_hi:[0,1]
	v_lshl_add_u64 v[142:143], v[132:133], 0, v[190:191]
	s_waitcnt vmcnt(8)
	v_pk_fma_f32 v[94:95], v[62:63], v[94:95], v[126:127]
	v_cvt_f32_i32_e32 v139, v91
	v_cvt_f32_i32_e32 v138, v90
	v_cvt_f32_i32_e32 v141, v93
	v_cvt_f32_i32_e32 v140, v92
	v_cvt_f32_i32_e32 v135, v87
	v_cvt_f32_i32_e32 v134, v86
	v_cvt_f32_i32_e32 v137, v89
	v_cvt_f32_i32_e32 v136, v88
	v_cvt_f32_i32_e32 v127, v83
	v_cvt_f32_i32_e32 v126, v82
	v_cvt_f32_i32_e32 v133, v85
	v_cvt_f32_i32_e32 v132, v84
	v_readlane_b32 s68, v254, 8
	v_pk_mul_f32 v[96:97], v[202:203], v[96:97] op_sel_hi:[0,1]
	v_readlane_b32 s74, v254, 14
	v_readlane_b32 s75, v254, 15
	v_pk_fma_f32 v[96:97], v[64:65], v[96:97], v[128:129]
	s_and_b64 vcc, exec, s[8:9]
	s_mov_b64 s[98:99], 0x3000
	v_lshl_add_u64 v[128:129], v[250:251], 0, s[98:99]
	v_readlane_b32 s69, v254, 9
	v_readlane_b32 s70, v254, 10
	v_readlane_b32 s71, v254, 11
	v_readlane_b32 s72, v254, 12
	v_readlane_b32 s73, v254, 13
	global_store_dwordx4 v[128:129], v[94:97], off
	s_cbranch_vccnz .LBB0_1786
	v_readlane_b32 s2, v254, 40
	v_lshlrev_b64 v[146:147], 1, v[142:143]
	v_readlane_b32 s3, v254, 41
	s_nop 0
	v_cvt_pk_bf16_f32 v82, v94, v95
	s_nop 0
	v_cvt_pk_bf16_f32 v83, v96, v97
	v_mov_b32_e32 v90, v202
	v_mov_b32_e32 v91, v202
	v_lshl_add_u64 v[84:85], s[2:3], 0, v[146:147]
	global_store_dwordx2 v[84:85], v[82:83], off
	v_mul_f32_e32 v82, v95, v95
	v_mul_f32_e32 v83, v97, v97
	v_fmac_f32_e32 v82, v94, v94
	v_fmac_f32_e32 v83, v96, v96
	v_add_f32_e32 v92, v82, v83
	v_pk_mul_f32 v[82:83], v[90:91], v[140:141]
	v_pk_mul_f32 v[86:87], v[202:203], v[138:139]
	s_waitcnt vmcnt(9)
	v_pk_fma_f32 v[84:85], v[44:45], v[82:83], v[124:125]
	v_pk_fma_f32 v[82:83], v[42:43], v[86:87], v[122:123]
	v_or_b32_e32 v88, 32, v146
	v_mov_b32_e32 v89, v147
	global_store_dwordx4 v[128:129], v[82:85], off offset:1024
	s_nop 0
	v_cvt_pk_bf16_f32 v86, v82, v83
	s_nop 0
	v_cvt_pk_bf16_f32 v87, v84, v85
	v_lshl_add_u64 v[88:89], s[2:3], 0, v[88:89]
	global_store_dwordx2 v[88:89], v[86:87], off
	v_mul_f32_e32 v86, v83, v83
	v_mul_f32_e32 v87, v85, v85
	v_fmac_f32_e32 v86, v82, v82
	v_fmac_f32_e32 v87, v84, v84
	v_add_f32_e32 v86, v86, v87
	v_add_f32_e32 v142, v92, v86
	v_pk_mul_f32 v[86:87], v[90:91], v[136:137]
	v_pk_mul_f32 v[92:93], v[202:203], v[134:135]
	s_waitcnt vmcnt(10)
	v_pk_fma_f32 v[88:89], v[40:41], v[86:87], v[120:121]
	v_pk_fma_f32 v[86:87], v[38:39], v[92:93], v[118:119]
	v_mul_f32_e32 v93, v89, v89
	v_mul_f32_e32 v92, v87, v87
	v_fmac_f32_e32 v92, v86, v86
	v_fmac_f32_e32 v93, v88, v88
	v_add_f32_e32 v92, v92, v93
	v_add_f32_e32 v150, v142, v92
	v_pk_mul_f32 v[90:91], v[90:91], v[132:133]
	v_pk_mul_f32 v[142:143], v[202:203], v[126:127]
	s_waitcnt vmcnt(9)
	v_pk_fma_f32 v[92:93], v[36:37], v[90:91], v[116:117]
	v_pk_fma_f32 v[90:91], v[34:35], v[142:143], v[114:115]
	v_mul_f32_e32 v143, v93, v93
	v_mul_f32_e32 v142, v91, v91
	v_fmac_f32_e32 v142, v90, v90
	v_fmac_f32_e32 v143, v92, v92
	v_add_f32_e32 v142, v142, v143
	v_add_f32_e32 v143, v150, v142
	v_and_b32_e32 v150, 64, v236
	v_xor_b32_e32 v142, 16, v236
	v_add_u32_e32 v150, 64, v150
	v_cmp_lt_i32_e32 vcc, v142, v150
	v_or_b32_e32 v148, 0x100, v146
	v_mov_b32_e32 v149, v147
	v_cndmask_b32_e32 v142, v236, v142, vcc
	v_lshlrev_b32_e32 v142, 2, v142
	ds_bpermute_b32 v151, v142, v143
	global_store_dwordx4 v[128:129], v[86:89], off offset:2048
	s_nop 0
	v_cvt_pk_bf16_f32 v144, v86, v87
	s_nop 0
	v_cvt_pk_bf16_f32 v145, v88, v89
	v_lshl_add_u64 v[148:149], s[2:3], 0, v[148:149]
	global_store_dwordx2 v[148:149], v[144:145], off
	global_store_dwordx4 v[128:129], v[90:93], off offset:3072
	s_waitcnt lgkmcnt(0)
	v_add_f32_e32 v144, v143, v151
	v_xor_b32_e32 v143, 32, v236
	v_cmp_lt_i32_e32 vcc, v143, v150
	v_or_b32_e32 v146, 0x120, v146
	v_lshl_add_u64 v[146:147], s[2:3], 0, v[146:147]
	v_cndmask_b32_e32 v143, v236, v143, vcc
	v_lshlrev_b32_e32 v143, 2, v143
	ds_bpermute_b32 v145, v143, v144
	s_nop 0
	v_cvt_pk_bf16_f32 v148, v90, v91
	s_nop 0
	v_cvt_pk_bf16_f32 v149, v92, v93
	global_store_dwordx2 v[146:147], v[148:149], off
	s_and_saveexec_b64 s[2:3], s[6:7]
	s_cbranch_execz .LBB0_1748
	v_lshl_add_u64 v[146:147], v[204:205], 2, s[10:11]
	s_waitcnt lgkmcnt(0)
	v_add_f32_e32 v144, v144, v145
	global_atomic_add_f32 v[146:147], v144, off

; __device__ __forceinline__ unsigned cvt_pk_bf16(float lo, float hi) { unsigned r; asm volatile("s_nop 0\n\tv_cvt_pk_bf16_f32 %0, %1, %2" : "=v"(r) : "v"(lo), "v"(hi)); return r; }
; __device__ __forceinline__ f32x4 sig4(const f32x4 v) { return (f32x4){sigmoidf_(v[0]), sigmoidf_(v[1]), sigmoidf_(v[2]), sigmoidf_(v[3])}; }
;     __device__ __forceinline__ void operator()(const typename AccT<I8>::type (&acc)[2][2][4][2], const Unit& u, int wr, int wc, int fr, int fq) const {
;     ...
;         for (int s = 0; s < 8; ++s) { const int ai = s >> 2, m = s & 3; const int r = row0 + ai * HALF + m * 16; const size_t off = (size_t)r * 4096 + col0;
;                 if (s + 1 < 8) load_row(nxt, (size_t)(row0 + ((s + 1) >> 2) * HALF + ((s + 1) & 3) * 16) * 4096 + col0);
;                 const float rs = rsv[s];
;                 float ss = 0.f, mx = 0.f;
; #pragma unroll
;                 for (int bj = 0; bj < 2; ++bj)
; #pragma unroll
;                     for (int n = 0; n < 2; ++n) { const size_t o = off + bj * HALF + n * 16; const f32x4 b = cur.b[bj][n]; f32x4 v;
;                         if constexpr (I8) v = __builtin_convertvector(acc[ai][bj][m][n], f32x4) * rs * sv[bj][n]; else v = acc[ai][bj][m][n];
;                         if (MODE == 1) { const u32x2 pw = cur.pw[bj][n]; const f32x4 pp = (f32x4){bf_lo(pw.x), bf_hi(pw.x), bf_lo(pw.y), bf_hi(pw.y)}; v = sig4(I8 ? v : v * rs) * pp; }
;                         const f32x4 x = b + v; *(f32x4*)(out + o) = x;
;                         if (MODE == 0 && XB) { u32x2 w; w.x = cvt_pk_bf16(x[0], x[1]); w.y = cvt_pk_bf16(x[2], x[3]); *(u32x2*)(XB + o) = w; ss += (x[0] * x[0] + x[1] * x[1]) + (x[2] * x[2] + x[3] * x[3]);
;                             if (RM) mx = fmaxf(fmaxf(mx, fmaxf(fabsf(x[0]), fabsf(x[1]))), fmaxf(fabsf(x[2]), fabsf(x[3]))); } }
;                 if (MODE == 0 && XB) { ss += __shfl_xor(ss, 16); ss += __shfl_xor(ss, 32); if (fq == 0) unsafeAtomicAdd(SS + r, ss);
;                     if (RM) { mx = fmaxf(mx, __shfl_xor(mx, 16)); mx = fmaxf(mx, __shfl_xor(mx, 32)); if (fq == 0) atomicMax(RM + r, __builtin_bit_cast(unsigned, mx)); } }
.LBB0_1751:
	v_mov_b32_e32 v86, v202
	v_mov_b32_e32 v87, v202
	s_waitcnt lgkmcnt(0)
	v_pk_mul_f32 v[82:83], v[86:87], v[140:141]
	v_pk_mul_f32 v[88:89], v[202:203], v[138:139]
	s_waitcnt vmcnt(8)
	v_pk_fma_f32 v[84:85], v[44:45], v[82:83], v[124:125]
	v_pk_fma_f32 v[82:83], v[42:43], v[88:89], v[122:123]
	global_store_dwordx4 v[128:129], v[82:85], off offset:1024
	v_pk_mul_f32 v[88:89], v[202:203], v[134:135]
	s_nop 0
	v_pk_mul_f32 v[82:83], v[86:87], v[136:137]
	s_waitcnt vmcnt(8)
	v_pk_fma_f32 v[84:85], v[40:41], v[82:83], v[120:121]
	v_pk_fma_f32 v[82:83], v[38:39], v[88:89], v[118:119]
	global_store_dwordx4 v[128:129], v[82:85], off offset:2048
	s_nop 1
	v_pk_mul_f32 v[82:83], v[86:87], v[132:133]
	v_pk_mul_f32 v[86:87], v[202:203], v[126:127]
	s_waitcnt vmcnt(8)
	v_pk_fma_f32 v[84:85], v[36:37], v[82:83], v[116:117]
	v_pk_fma_f32 v[82:83], v[34:35], v[86:87], v[114:115]
	global_store_dwordx4 v[128:129], v[82:85], off offset:3072
.LBB0_1752:
	s_waitcnt lgkmcnt(0)
	s_nop 0
	v_lshlrev_b64 v[82:83], 14, v[198:199]
	v_lshl_add_u64 v[82:83], s[64:65], 0, v[82:83]
	v_lshl_add_u64 v[82:83], v[190:191], 2, v[82:83]
	global_load_dwordx4 v[94:97], v[82:83], off
	global_load_dwordx4 v[90:93], v[82:83], off offset:64
	global_load_dwordx4 v[86:89], v[82:83], off offset:512
	s_nop 0
	global_load_dwordx4 v[82:85], v[82:83], off offset:576
	v_cvt_f32_i32_e32 v79, v79
	v_cvt_f32_i32_e32 v78, v78
	v_cvt_f32_i32_e32 v81, v81
	v_cvt_f32_i32_e32 v80, v80
	v_mov_b32_e32 v201, v200
	s_waitcnt vmcnt(10)
	v_lshlrev_b64 v[114:115], 12, v[130:131]
	v_pk_mul_f32 v[78:79], v[200:201], v[78:79] op_sel_hi:[0,1]
	v_lshl_add_u64 v[124:125], v[114:115], 0, v[190:191]
	s_waitcnt vmcnt(8)
	v_pk_fma_f32 v[78:79], v[62:63], v[78:79], v[110:111]
	v_cvt_f32_i32_e32 v121, v75
	v_cvt_f32_i32_e32 v120, v74
	v_cvt_f32_i32_e32 v123, v77
	v_cvt_f32_i32_e32 v122, v76
	v_cvt_f32_i32_e32 v117, v71
	v_cvt_f32_i32_e32 v116, v70
	v_cvt_f32_i32_e32 v119, v73
	v_cvt_f32_i32_e32 v118, v72
	v_cvt_f32_i32_e32 v111, v67
	v_cvt_f32_i32_e32 v110, v66
	v_cvt_f32_i32_e32 v115, v69
	v_cvt_f32_i32_e32 v114, v68
	v_readlane_b32 s68, v254, 8
	v_pk_mul_f32 v[80:81], v[200:201], v[80:81] op_sel_hi:[0,1]
	v_readlane_b32 s74, v254, 14
	v_readlane_b32 s75, v254, 15
	v_pk_fma_f32 v[80:81], v[64:65], v[80:81], v[112:113]
	s_and_b64 vcc, exec, s[8:9]
	s_mov_b64 s[98:99], 0x4000
	v_lshl_add_u64 v[112:113], v[250:251], 0, s[98:99]
	v_readlane_b32 s69, v254, 9
	v_readlane_b32 s70, v254, 10
	v_readlane_b32 s71, v254, 11
	v_readlane_b32 s72, v254, 12
	v_readlane_b32 s73, v254, 13
	global_store_dwordx4 v[112:113], v[78:81], off
	s_cbranch_vccnz .LBB0_1787
	v_readlane_b32 s2, v254, 40
	v_lshlrev_b64 v[128:129], 1, v[124:125]
	v_readlane_b32 s3, v254, 41
	s_nop 0
	v_cvt_pk_bf16_f32 v66, v78, v79
	s_nop 0
	v_cvt_pk_bf16_f32 v67, v80, v81
	v_mov_b32_e32 v74, v200
	v_mov_b32_e32 v75, v200
	v_lshl_add_u64 v[68:69], s[2:3], 0, v[128:129]
	global_store_dwordx2 v[68:69], v[66:67], off
	v_mul_f32_e32 v66, v79, v79
	v_mul_f32_e32 v67, v81, v81
	v_fmac_f32_e32 v66, v78, v78
	v_fmac_f32_e32 v67, v80, v80
	v_add_f32_e32 v76, v66, v67
	v_pk_mul_f32 v[66:67], v[74:75], v[122:123]
	v_pk_mul_f32 v[70:71], v[200:201], v[120:121]
	s_waitcnt vmcnt(9)
	v_pk_fma_f32 v[68:69], v[44:45], v[66:67], v[108:109]
	v_pk_fma_f32 v[66:67], v[42:43], v[70:71], v[106:107]
	v_or_b32_e32 v72, 32, v128
	v_mov_b32_e32 v73, v129
	global_store_dwordx4 v[112:113], v[66:69], off offset:1024
	s_nop 0
	v_cvt_pk_bf16_f32 v70, v66, v67
	s_nop 0
	v_cvt_pk_bf16_f32 v71, v68, v69
	v_lshl_add_u64 v[72:73], s[2:3], 0, v[72:73]
	global_store_dwordx2 v[72:73], v[70:71], off
	v_mul_f32_e32 v70, v67, v67
	v_mul_f32_e32 v71, v69, v69
	v_fmac_f32_e32 v70, v66, v66
	v_fmac_f32_e32 v71, v68, v68
	v_add_f32_e32 v70, v70, v71
	v_add_f32_e32 v124, v76, v70
	v_pk_mul_f32 v[70:71], v[74:75], v[118:119]
	v_pk_mul_f32 v[76:77], v[200:201], v[116:117]
	s_waitcnt vmcnt(10)
	v_pk_fma_f32 v[72:73], v[40:41], v[70:71], v[104:105]
	v_pk_fma_f32 v[70:71], v[38:39], v[76:77], v[102:103]
	v_mul_f32_e32 v77, v73, v73
	v_mul_f32_e32 v76, v71, v71
	v_fmac_f32_e32 v76, v70, v70
	v_fmac_f32_e32 v77, v72, v72
	v_add_f32_e32 v76, v76, v77
	v_add_f32_e32 v134, v124, v76
	v_pk_mul_f32 v[74:75], v[74:75], v[114:115]
	v_pk_mul_f32 v[124:125], v[200:201], v[110:111]
	s_waitcnt vmcnt(9)
	v_pk_fma_f32 v[76:77], v[36:37], v[74:75], v[100:101]
	v_pk_fma_f32 v[74:75], v[34:35], v[124:125], v[98:99]
	v_mul_f32_e32 v125, v77, v77
	v_mul_f32_e32 v124, v75, v75
	v_fmac_f32_e32 v124, v74, v74
	v_fmac_f32_e32 v125, v76, v76
	v_add_f32_e32 v124, v124, v125
	v_add_f32_e32 v125, v134, v124
	v_and_b32_e32 v134, 64, v236
	v_xor_b32_e32 v124, 16, v236
	v_add_u32_e32 v134, 64, v134
	v_cmp_lt_i32_e32 vcc, v124, v134
	v_or_b32_e32 v132, 0x100, v128
	v_mov_b32_e32 v133, v129
	v_cndmask_b32_e32 v124, v236, v124, vcc
	v_lshlrev_b32_e32 v124, 2, v124
	ds_bpermute_b32 v135, v124, v125
	global_store_dwordx4 v[112:113], v[70:73], off offset:2048
	s_nop 0
	v_cvt_pk_bf16_f32 v126, v70, v71
	s_nop 0
	v_cvt_pk_bf16_f32 v127, v72, v73
	v_lshl_add_u64 v[132:133], s[2:3], 0, v[132:133]
	global_store_dwordx2 v[132:133], v[126:127], off
	global_store_dwordx4 v[112:113], v[74:77], off offset:3072
	s_waitcnt lgkmcnt(0)
	v_add_f32_e32 v126, v125, v135
	v_xor_b32_e32 v125, 32, v236
	v_cmp_lt_i32_e32 vcc, v125, v134
	v_or_b32_e32 v128, 0x120, v128
	v_lshl_add_u64 v[128:129], s[2:3], 0, v[128:129]
	v_cndmask_b32_e32 v125, v236, v125, vcc
	v_lshlrev_b32_e32 v125, 2, v125
	ds_bpermute_b32 v127, v125, v126
	s_nop 0
	v_cvt_pk_bf16_f32 v132, v74, v75
	s_nop 0
	v_cvt_pk_bf16_f32 v133, v76, v77
	global_store_dwordx2 v[128:129], v[132:133], off
	s_and_saveexec_b64 s[2:3], s[6:7]
	s_cbranch_execz .LBB0_1755
	v_lshl_add_u64 v[128:129], v[130:131], 2, s[10:11]
	s_waitcnt lgkmcnt(0)
	v_add_f32_e32 v126, v126, v127
	global_atomic_add_f32 v[128:129], v126, off

; __device__ __forceinline__ unsigned cvt_pk_bf16(float lo, float hi) { unsigned r; asm volatile("s_nop 0\n\tv_cvt_pk_bf16_f32 %0, %1, %2" : "=v"(r) : "v"(lo), "v"(hi)); return r; }
; __device__ __forceinline__ f32x4 sig4(const f32x4 v) { return (f32x4){sigmoidf_(v[0]), sigmoidf_(v[1]), sigmoidf_(v[2]), sigmoidf_(v[3])}; }
;     __device__ __forceinline__ void operator()(const typename AccT<I8>::type (&acc)[2][2][4][2], const Unit& u, int wr, int wc, int fr, int fq) const {
;     ...
;         for (int s = 0; s < 8; ++s) { const int ai = s >> 2, m = s & 3; const int r = row0 + ai * HALF + m * 16; const size_t off = (size_t)r * 4096 + col0;
;                 if (s + 1 < 8) load_row(nxt, (size_t)(row0 + ((s + 1) >> 2) * HALF + ((s + 1) & 3) * 16) * 4096 + col0);
;                 const float rs = rsv[s];
;                 float ss = 0.f, mx = 0.f;
; #pragma unroll
;                 for (int bj = 0; bj < 2; ++bj)
; #pragma unroll
;                     for (int n = 0; n < 2; ++n) { const size_t o = off + bj * HALF + n * 16; const f32x4 b = cur.b[bj][n]; f32x4 v;
;                         if constexpr (I8) v = __builtin_convertvector(acc[ai][bj][m][n], f32x4) * rs * sv[bj][n]; else v = acc[ai][bj][m][n];
;                         if (MODE == 1) { const u32x2 pw = cur.pw[bj][n]; const f32x4 pp = (f32x4){bf_lo(pw.x), bf_hi(pw.x), bf_lo(pw.y), bf_hi(pw.y)}; v = sig4(I8 ? v : v * rs) * pp; }
;                         const f32x4 x = b + v; *(f32x4*)(out + o) = x;
;                         if (MODE == 0 && XB) { u32x2 w; w.x = cvt_pk_bf16(x[0], x[1]); w.y = cvt_pk_bf16(x[2], x[3]); *(u32x2*)(XB + o) = w; ss += (x[0] * x[0] + x[1] * x[1]) + (x[2] * x[2] + x[3] * x[3]);
;                             if (RM) mx = fmaxf(fmaxf(mx, fmaxf(fabsf(x[0]), fabsf(x[1]))), fmaxf(fabsf(x[2]), fabsf(x[3]))); } }
;                 if (MODE == 0 && XB) { ss += __shfl_xor(ss, 16); ss += __shfl_xor(ss, 32); if (fq == 0) unsafeAtomicAdd(SS + r, ss);
;                     if (RM) { mx = fmaxf(mx, __shfl_xor(mx, 16)); mx = fmaxf(mx, __shfl_xor(mx, 32)); if (fq == 0) atomicMax(RM + r, __builtin_bit_cast(unsigned, mx)); } }
.LBB0_1758:
	v_mov_b32_e32 v70, v200
	v_mov_b32_e32 v71, v200
	s_waitcnt lgkmcnt(0)
	v_pk_mul_f32 v[66:67], v[70:71], v[122:123]
	v_pk_mul_f32 v[72:73], v[200:201], v[120:121]
	s_waitcnt vmcnt(8)
	v_pk_fma_f32 v[68:69], v[44:45], v[66:67], v[108:109]
	v_pk_fma_f32 v[66:67], v[42:43], v[72:73], v[106:107]
	global_store_dwordx4 v[112:113], v[66:69], off offset:1024
	v_pk_mul_f32 v[72:73], v[200:201], v[116:117]
	s_nop 0
	v_pk_mul_f32 v[66:67], v[70:71], v[118:119]
	s_waitcnt vmcnt(8)
	v_pk_fma_f32 v[68:69], v[40:41], v[66:67], v[104:105]
	v_pk_fma_f32 v[66:67], v[38:39], v[72:73], v[102:103]
	global_store_dwordx4 v[112:113], v[66:69], off offset:2048
	s_nop 1
	v_pk_mul_f32 v[66:67], v[70:71], v[114:115]
	v_pk_mul_f32 v[70:71], v[200:201], v[110:111]
	s_waitcnt vmcnt(8)
	v_pk_fma_f32 v[68:69], v[36:37], v[66:67], v[100:101]
	v_pk_fma_f32 v[66:67], v[34:35], v[70:71], v[98:99]
	global_store_dwordx4 v[112:113], v[66:69], off offset:3072
.LBB0_1759:
	s_waitcnt lgkmcnt(0)
	s_nop 0
	v_lshlrev_b64 v[66:67], 14, v[194:195]
	v_lshl_add_u64 v[66:67], s[64:65], 0, v[66:67]
	v_lshl_add_u64 v[66:67], v[190:191], 2, v[66:67]
	global_load_dwordx4 v[78:81], v[66:67], off
	global_load_dwordx4 v[74:77], v[66:67], off offset:64
	global_load_dwordx4 v[70:73], v[66:67], off offset:512
	s_nop 0
	global_load_dwordx4 v[66:69], v[66:67], off offset:576
	v_cvt_f32_i32_e32 v59, v59
	v_cvt_f32_i32_e32 v58, v58
	v_cvt_f32_i32_e32 v61, v61
	v_cvt_f32_i32_e32 v60, v60
	v_mov_b32_e32 v197, v196
	s_waitcnt vmcnt(10)
	v_lshlrev_b64 v[98:99], 12, v[198:199]
	v_pk_mul_f32 v[58:59], v[196:197], v[58:59] op_sel_hi:[0,1]
	v_lshl_add_u64 v[108:109], v[98:99], 0, v[190:191]
	s_waitcnt vmcnt(8)
	v_pk_fma_f32 v[58:59], v[62:63], v[58:59], v[94:95]
	v_cvt_f32_i32_e32 v105, v55
	v_cvt_f32_i32_e32 v104, v54
	v_cvt_f32_i32_e32 v107, v57
	v_cvt_f32_i32_e32 v106, v56
	v_cvt_f32_i32_e32 v101, v51
	v_cvt_f32_i32_e32 v100, v50
	v_cvt_f32_i32_e32 v103, v53
	v_cvt_f32_i32_e32 v102, v52
	v_cvt_f32_i32_e32 v95, v47
	v_cvt_f32_i32_e32 v94, v46
	v_cvt_f32_i32_e32 v99, v49
	v_cvt_f32_i32_e32 v98, v48
	v_readlane_b32 s68, v254, 8
	v_pk_mul_f32 v[60:61], v[196:197], v[60:61] op_sel_hi:[0,1]
	v_readlane_b32 s74, v254, 14
	v_readlane_b32 s75, v254, 15
	v_pk_fma_f32 v[60:61], v[64:65], v[60:61], v[96:97]
	s_and_b64 vcc, exec, s[8:9]
	s_mov_b64 s[98:99], 0x5000
	v_lshl_add_u64 v[96:97], v[250:251], 0, s[98:99]
	v_readlane_b32 s69, v254, 9
	v_readlane_b32 s70, v254, 10
	v_readlane_b32 s71, v254, 11
	v_readlane_b32 s72, v254, 12
	v_readlane_b32 s73, v254, 13
	global_store_dwordx4 v[96:97], v[58:61], off
	s_cbranch_vccnz .LBB0_1788
	v_readlane_b32 s2, v254, 40
	v_lshlrev_b64 v[112:113], 1, v[108:109]
	v_readlane_b32 s3, v254, 41
	s_nop 0
	v_cvt_pk_bf16_f32 v46, v58, v59
	s_nop 0
	v_cvt_pk_bf16_f32 v47, v60, v61
	v_mov_b32_e32 v54, v196
	v_mov_b32_e32 v55, v196
	v_lshl_add_u64 v[48:49], s[2:3], 0, v[112:113]
	global_store_dwordx2 v[48:49], v[46:47], off
	v_mul_f32_e32 v46, v59, v59
	v_mul_f32_e32 v47, v61, v61
	v_fmac_f32_e32 v46, v58, v58
	v_fmac_f32_e32 v47, v60, v60
	v_add_f32_e32 v56, v46, v47
	v_pk_mul_f32 v[46:47], v[54:55], v[106:107]
	v_pk_mul_f32 v[50:51], v[196:197], v[104:105]
	s_waitcnt vmcnt(9)
	v_pk_fma_f32 v[48:49], v[44:45], v[46:47], v[92:93]
	v_pk_fma_f32 v[46:47], v[42:43], v[50:51], v[90:91]
	v_or_b32_e32 v52, 32, v112
	v_mov_b32_e32 v53, v113
	global_store_dwordx4 v[96:97], v[46:49], off offset:1024
	s_nop 0
	v_cvt_pk_bf16_f32 v50, v46, v47
	s_nop 0
	v_cvt_pk_bf16_f32 v51, v48, v49
	v_lshl_add_u64 v[52:53], s[2:3], 0, v[52:53]
	global_store_dwordx2 v[52:53], v[50:51], off
	v_mul_f32_e32 v50, v47, v47
	v_mul_f32_e32 v51, v49, v49
	v_fmac_f32_e32 v50, v46, v46
	v_fmac_f32_e32 v51, v48, v48
	v_add_f32_e32 v50, v50, v51
	v_add_f32_e32 v108, v56, v50
	v_pk_mul_f32 v[50:51], v[54:55], v[102:103]
	v_pk_mul_f32 v[56:57], v[196:197], v[100:101]
	s_waitcnt vmcnt(10)
	v_pk_fma_f32 v[52:53], v[40:41], v[50:51], v[88:89]
	v_pk_fma_f32 v[50:51], v[38:39], v[56:57], v[86:87]
	v_mul_f32_e32 v57, v53, v53
	v_mul_f32_e32 v56, v51, v51
	v_fmac_f32_e32 v56, v50, v50
	v_fmac_f32_e32 v57, v52, v52
	v_add_f32_e32 v56, v56, v57
	v_add_f32_e32 v116, v108, v56
	v_pk_mul_f32 v[54:55], v[54:55], v[98:99]
	v_pk_mul_f32 v[108:109], v[196:197], v[94:95]
	s_waitcnt vmcnt(9)
	v_pk_fma_f32 v[56:57], v[36:37], v[54:55], v[84:85]
	v_pk_fma_f32 v[54:55], v[34:35], v[108:109], v[82:83]
	v_mul_f32_e32 v109, v57, v57
	v_mul_f32_e32 v108, v55, v55
	v_fmac_f32_e32 v108, v54, v54
	v_fmac_f32_e32 v109, v56, v56
	v_add_f32_e32 v108, v108, v109
	v_add_f32_e32 v109, v116, v108
	v_and_b32_e32 v116, 64, v236
	v_xor_b32_e32 v108, 16, v236
	v_add_u32_e32 v116, 64, v116
	v_cmp_lt_i32_e32 vcc, v108, v116
	v_or_b32_e32 v114, 0x100, v112
	v_mov_b32_e32 v115, v113
	v_cndmask_b32_e32 v108, v236, v108, vcc
	v_lshlrev_b32_e32 v108, 2, v108
	ds_bpermute_b32 v117, v108, v109
	global_store_dwordx4 v[96:97], v[50:53], off offset:2048
	s_nop 0
	v_cvt_pk_bf16_f32 v110, v50, v51
	s_nop 0
	v_cvt_pk_bf16_f32 v111, v52, v53
	v_lshl_add_u64 v[114:115], s[2:3], 0, v[114:115]
	global_store_dwordx2 v[114:115], v[110:111], off
	global_store_dwordx4 v[96:97], v[54:57], off offset:3072
	s_waitcnt lgkmcnt(0)
	v_add_f32_e32 v110, v109, v117
	v_xor_b32_e32 v109, 32, v236
	v_cmp_lt_i32_e32 vcc, v109, v116
	v_or_b32_e32 v112, 0x120, v112
	v_lshl_add_u64 v[112:113], s[2:3], 0, v[112:113]
	v_cndmask_b32_e32 v109, v236, v109, vcc
	v_lshlrev_b32_e32 v109, 2, v109
	ds_bpermute_b32 v111, v109, v110
	s_nop 0
	v_cvt_pk_bf16_f32 v114, v54, v55
	s_nop 0
	v_cvt_pk_bf16_f32 v115, v56, v57
	global_store_dwordx2 v[112:113], v[114:115], off
	s_and_saveexec_b64 s[2:3], s[6:7]
	s_cbranch_execz .LBB0_1762
	v_lshl_add_u64 v[112:113], v[198:199], 2, s[10:11]
	s_waitcnt lgkmcnt(0)
	v_add_f32_e32 v110, v110, v111
	global_atomic_add_f32 v[112:113], v110, off

; __device__ __forceinline__ unsigned cvt_pk_bf16(float lo, float hi) { unsigned r; asm volatile("s_nop 0\n\tv_cvt_pk_bf16_f32 %0, %1, %2" : "=v"(r) : "v"(lo), "v"(hi)); return r; }
; __device__ __forceinline__ f32x4 sig4(const f32x4 v) { return (f32x4){sigmoidf_(v[0]), sigmoidf_(v[1]), sigmoidf_(v[2]), sigmoidf_(v[3])}; }
;     __device__ __forceinline__ void operator()(const typename AccT<I8>::type (&acc)[2][2][4][2], const Unit& u, int wr, int wc, int fr, int fq) const {
;     ...
;         for (int s = 0; s < 8; ++s) { const int ai = s >> 2, m = s & 3; const int r = row0 + ai * HALF + m * 16; const size_t off = (size_t)r * 4096 + col0;
;                 if (s + 1 < 8) load_row(nxt, (size_t)(row0 + ((s + 1) >> 2) * HALF + ((s + 1) & 3) * 16) * 4096 + col0);
;                 const float rs = rsv[s];
;                 float ss = 0.f, mx = 0.f;
; #pragma unroll
;                 for (int bj = 0; bj < 2; ++bj)
; #pragma unroll
;                     for (int n = 0; n < 2; ++n) { const size_t o = off + bj * HALF + n * 16; const f32x4 b = cur.b[bj][n]; f32x4 v;
;                         if constexpr (I8) v = __builtin_convertvector(acc[ai][bj][m][n], f32x4) * rs * sv[bj][n]; else v = acc[ai][bj][m][n];
;                         if (MODE == 1) { const u32x2 pw = cur.pw[bj][n]; const f32x4 pp = (f32x4){bf_lo(pw.x), bf_hi(pw.x), bf_lo(pw.y), bf_hi(pw.y)}; v = sig4(I8 ? v : v * rs) * pp; }
;                         const f32x4 x = b + v; *(f32x4*)(out + o) = x;
;                         if (MODE == 0 && XB) { u32x2 w; w.x = cvt_pk_bf16(x[0], x[1]); w.y = cvt_pk_bf16(x[2], x[3]); *(u32x2*)(XB + o) = w; ss += (x[0] * x[0] + x[1] * x[1]) + (x[2] * x[2] + x[3] * x[3]);
;                             if (RM) mx = fmaxf(fmaxf(mx, fmaxf(fabsf(x[0]), fabsf(x[1]))), fmaxf(fabsf(x[2]), fabsf(x[3]))); } }
;                 if (MODE == 0 && XB) { ss += __shfl_xor(ss, 16); ss += __shfl_xor(ss, 32); if (fq == 0) unsafeAtomicAdd(SS + r, ss);
;                     if (RM) { mx = fmaxf(mx, __shfl_xor(mx, 16)); mx = fmaxf(mx, __shfl_xor(mx, 32)); if (fq == 0) atomicMax(RM + r, __builtin_bit_cast(unsigned, mx)); } }
.LBB0_1765:
	v_mov_b32_e32 v50, v196
	v_mov_b32_e32 v51, v196
	s_waitcnt lgkmcnt(0)
	v_pk_mul_f32 v[46:47], v[50:51], v[106:107]
	v_pk_mul_f32 v[52:53], v[196:197], v[104:105]
	s_waitcnt vmcnt(8)
	v_pk_fma_f32 v[48:49], v[44:45], v[46:47], v[92:93]
	v_pk_fma_f32 v[46:47], v[42:43], v[52:53], v[90:91]
	global_store_dwordx4 v[96:97], v[46:49], off offset:1024
	v_pk_mul_f32 v[52:53], v[196:197], v[100:101]
	s_nop 0
	v_pk_mul_f32 v[46:47], v[50:51], v[102:103]
	s_waitcnt vmcnt(8)
	v_pk_fma_f32 v[48:49], v[40:41], v[46:47], v[88:89]
	v_pk_fma_f32 v[46:47], v[38:39], v[52:53], v[86:87]
	global_store_dwordx4 v[96:97], v[46:49], off offset:2048
	s_nop 1
	v_pk_mul_f32 v[46:47], v[50:51], v[98:99]
	v_pk_mul_f32 v[50:51], v[196:197], v[94:95]
	s_waitcnt vmcnt(8)
	v_pk_fma_f32 v[48:49], v[36:37], v[46:47], v[84:85]
	v_pk_fma_f32 v[46:47], v[34:35], v[50:51], v[82:83]
	global_store_dwordx4 v[96:97], v[46:49], off offset:3072
.LBB0_1766:
	s_waitcnt lgkmcnt(0)
	s_nop 0
	v_lshlrev_b64 v[46:47], 14, v[188:189]
	v_lshl_add_u64 v[46:47], s[64:65], 0, v[46:47]
	v_lshl_add_u64 v[46:47], v[190:191], 2, v[46:47]
	global_load_dwordx4 v[58:61], v[46:47], off
	global_load_dwordx4 v[54:57], v[46:47], off offset:64
	global_load_dwordx4 v[50:53], v[46:47], off offset:512
	s_nop 0
	global_load_dwordx4 v[46:49], v[46:47], off offset:576
	v_cvt_f32_i32_e32 v31, v31
	v_cvt_f32_i32_e32 v30, v30
	v_cvt_f32_i32_e32 v33, v33
	v_cvt_f32_i32_e32 v32, v32
	v_mov_b32_e32 v193, v192
	s_waitcnt vmcnt(10)
	v_lshlrev_b64 v[82:83], 12, v[194:195]
	v_pk_mul_f32 v[30:31], v[192:193], v[30:31] op_sel_hi:[0,1]
	v_lshl_add_u64 v[92:93], v[82:83], 0, v[190:191]
	s_waitcnt vmcnt(8)
	v_pk_fma_f32 v[30:31], v[62:63], v[30:31], v[78:79]
	v_cvt_f32_i32_e32 v89, v27
	v_cvt_f32_i32_e32 v88, v26
	v_cvt_f32_i32_e32 v91, v29
	v_cvt_f32_i32_e32 v90, v28
	v_cvt_f32_i32_e32 v85, v23
	v_cvt_f32_i32_e32 v84, v22
	v_cvt_f32_i32_e32 v87, v25
	v_cvt_f32_i32_e32 v86, v24
	v_cvt_f32_i32_e32 v79, v19
	v_cvt_f32_i32_e32 v78, v18
	v_cvt_f32_i32_e32 v83, v21
	v_cvt_f32_i32_e32 v82, v20
	v_readlane_b32 s68, v254, 8
	v_pk_mul_f32 v[32:33], v[192:193], v[32:33] op_sel_hi:[0,1]
	v_readlane_b32 s74, v254, 14
	v_readlane_b32 s75, v254, 15
	v_pk_fma_f32 v[32:33], v[64:65], v[32:33], v[80:81]
	s_and_b64 vcc, exec, s[8:9]
	s_mov_b64 s[98:99], 0x6000
	v_lshl_add_u64 v[80:81], v[250:251], 0, s[98:99]
	v_readlane_b32 s69, v254, 9
	v_readlane_b32 s70, v254, 10
	v_readlane_b32 s71, v254, 11
	v_readlane_b32 s72, v254, 12
	v_readlane_b32 s73, v254, 13
	global_store_dwordx4 v[80:81], v[30:33], off
	s_cbranch_vccnz .LBB0_1789
	v_readlane_b32 s2, v254, 40
	v_lshlrev_b64 v[96:97], 1, v[92:93]
	v_readlane_b32 s3, v254, 41
	s_nop 0
	v_cvt_pk_bf16_f32 v18, v30, v31
	s_nop 0
	v_cvt_pk_bf16_f32 v19, v32, v33
	v_mov_b32_e32 v26, v192
	v_mov_b32_e32 v27, v192
	v_lshl_add_u64 v[20:21], s[2:3], 0, v[96:97]
	global_store_dwordx2 v[20:21], v[18:19], off
	v_mul_f32_e32 v18, v31, v31
	v_mul_f32_e32 v19, v33, v33
	v_fmac_f32_e32 v18, v30, v30
	v_fmac_f32_e32 v19, v32, v32
	v_add_f32_e32 v28, v18, v19
	v_pk_mul_f32 v[18:19], v[26:27], v[90:91]
	v_pk_mul_f32 v[22:23], v[192:193], v[88:89]
	s_waitcnt vmcnt(9)
	v_pk_fma_f32 v[20:21], v[44:45], v[18:19], v[76:77]
	v_pk_fma_f32 v[18:19], v[42:43], v[22:23], v[74:75]
	v_or_b32_e32 v24, 32, v96
	v_mov_b32_e32 v25, v97
	global_store_dwordx4 v[80:81], v[18:21], off offset:1024
	s_nop 0
	v_cvt_pk_bf16_f32 v22, v18, v19
	s_nop 0
	v_cvt_pk_bf16_f32 v23, v20, v21
	v_lshl_add_u64 v[24:25], s[2:3], 0, v[24:25]
	global_store_dwordx2 v[24:25], v[22:23], off
	v_mul_f32_e32 v22, v19, v19
	v_mul_f32_e32 v23, v21, v21
	v_fmac_f32_e32 v22, v18, v18
	v_fmac_f32_e32 v23, v20, v20
	v_add_f32_e32 v22, v22, v23
	v_add_f32_e32 v92, v28, v22
	v_pk_mul_f32 v[22:23], v[26:27], v[86:87]
	v_pk_mul_f32 v[28:29], v[192:193], v[84:85]
	s_waitcnt vmcnt(10)
	v_pk_fma_f32 v[24:25], v[40:41], v[22:23], v[72:73]
	v_pk_fma_f32 v[22:23], v[38:39], v[28:29], v[70:71]
	v_mul_f32_e32 v29, v25, v25
	v_mul_f32_e32 v28, v23, v23
	v_fmac_f32_e32 v28, v22, v22
	v_fmac_f32_e32 v29, v24, v24
	v_add_f32_e32 v28, v28, v29
	v_add_f32_e32 v100, v92, v28
	v_pk_mul_f32 v[26:27], v[26:27], v[82:83]
	v_pk_mul_f32 v[92:93], v[192:193], v[78:79]
	s_waitcnt vmcnt(9)
	v_pk_fma_f32 v[28:29], v[36:37], v[26:27], v[68:69]
	v_pk_fma_f32 v[26:27], v[34:35], v[92:93], v[66:67]
	v_mul_f32_e32 v93, v29, v29
	v_mul_f32_e32 v92, v27, v27
	v_fmac_f32_e32 v92, v26, v26
	v_fmac_f32_e32 v93, v28, v28
	v_add_f32_e32 v92, v92, v93
	v_add_f32_e32 v93, v100, v92
	v_and_b32_e32 v100, 64, v236
	v_xor_b32_e32 v92, 16, v236
	v_add_u32_e32 v100, 64, v100
	v_cmp_lt_i32_e32 vcc, v92, v100
	v_or_b32_e32 v98, 0x100, v96
	v_mov_b32_e32 v99, v97
	v_cndmask_b32_e32 v92, v236, v92, vcc
	v_lshlrev_b32_e32 v92, 2, v92
	ds_bpermute_b32 v101, v92, v93
	global_store_dwordx4 v[80:81], v[22:25], off offset:2048
	s_nop 0
	v_cvt_pk_bf16_f32 v94, v22, v23
	s_nop 0
	v_cvt_pk_bf16_f32 v95, v24, v25
	v_lshl_add_u64 v[98:99], s[2:3], 0, v[98:99]
	global_store_dwordx2 v[98:99], v[94:95], off
	global_store_dwordx4 v[80:81], v[26:29], off offset:3072
	s_waitcnt lgkmcnt(0)
	v_add_f32_e32 v94, v93, v101
	v_xor_b32_e32 v93, 32, v236
	v_cmp_lt_i32_e32 vcc, v93, v100
	v_or_b32_e32 v96, 0x120, v96
	v_lshl_add_u64 v[96:97], s[2:3], 0, v[96:97]
	v_cndmask_b32_e32 v93, v236, v93, vcc
	v_lshlrev_b32_e32 v93, 2, v93
	ds_bpermute_b32 v95, v93, v94
	s_nop 0
	v_cvt_pk_bf16_f32 v98, v26, v27
	s_nop 0
	v_cvt_pk_bf16_f32 v99, v28, v29
	global_store_dwordx2 v[96:97], v[98:99], off
	s_and_saveexec_b64 s[2:3], s[6:7]
	s_cbranch_execz .LBB0_1769
	v_lshl_add_u64 v[96:97], v[194:195], 2, s[10:11]
	s_waitcnt lgkmcnt(0)
	v_add_f32_e32 v94, v94, v95
	global_atomic_add_f32 v[96:97], v94, off

; __device__ __forceinline__ unsigned cvt_pk_bf16(float lo, float hi) { unsigned r; asm volatile("s_nop 0\n\tv_cvt_pk_bf16_f32 %0, %1, %2" : "=v"(r) : "v"(lo), "v"(hi)); return r; }
; __device__ __forceinline__ f32x4 sig4(const f32x4 v) { return (f32x4){sigmoidf_(v[0]), sigmoidf_(v[1]), sigmoidf_(v[2]), sigmoidf_(v[3])}; }
;     __device__ __forceinline__ void operator()(const typename AccT<I8>::type (&acc)[2][2][4][2], const Unit& u, int wr, int wc, int fr, int fq) const {
;     ...
;         for (int s = 0; s < 8; ++s) { const int ai = s >> 2, m = s & 3; const int r = row0 + ai * HALF + m * 16; const size_t off = (size_t)r * 4096 + col0;
;                 if (s + 1 < 8) load_row(nxt, (size_t)(row0 + ((s + 1) >> 2) * HALF + ((s + 1) & 3) * 16) * 4096 + col0);
;                 const float rs = rsv[s];
;                 float ss = 0.f, mx = 0.f;
; #pragma unroll
;                 for (int bj = 0; bj < 2; ++bj)
; #pragma unroll
;                     for (int n = 0; n < 2; ++n) { const size_t o = off + bj * HALF + n * 16; const f32x4 b = cur.b[bj][n]; f32x4 v;
;                         if constexpr (I8) v = __builtin_convertvector(acc[ai][bj][m][n], f32x4) * rs * sv[bj][n]; else v = acc[ai][bj][m][n];
;                         if (MODE == 1) { const u32x2 pw = cur.pw[bj][n]; const f32x4 pp = (f32x4){bf_lo(pw.x), bf_hi(pw.x), bf_lo(pw.y), bf_hi(pw.y)}; v = sig4(I8 ? v : v * rs) * pp; }
;                         const f32x4 x = b + v; *(f32x4*)(out + o) = x;
;                         if (MODE == 0 && XB) { u32x2 w; w.x = cvt_pk_bf16(x[0], x[1]); w.y = cvt_pk_bf16(x[2], x[3]); *(u32x2*)(XB + o) = w; ss += (x[0] * x[0] + x[1] * x[1]) + (x[2] * x[2] + x[3] * x[3]);
;                             if (RM) mx = fmaxf(fmaxf(mx, fmaxf(fabsf(x[0]), fabsf(x[1]))), fmaxf(fabsf(x[2]), fabsf(x[3]))); } }
;                 if (MODE == 0 && XB) { ss += __shfl_xor(ss, 16); ss += __shfl_xor(ss, 32); if (fq == 0) unsafeAtomicAdd(SS + r, ss);
;                     if (RM) { mx = fmaxf(mx, __shfl_xor(mx, 16)); mx = fmaxf(mx, __shfl_xor(mx, 32)); if (fq == 0) atomicMax(RM + r, __builtin_bit_cast(unsigned, mx)); } }
.LBB0_1772:
	v_mov_b32_e32 v22, v192
	v_mov_b32_e32 v23, v192
	s_waitcnt lgkmcnt(0)
	v_pk_mul_f32 v[18:19], v[22:23], v[90:91]
	v_pk_mul_f32 v[24:25], v[192:193], v[88:89]
	s_waitcnt vmcnt(8)
	v_pk_fma_f32 v[20:21], v[44:45], v[18:19], v[76:77]
	v_pk_fma_f32 v[18:19], v[42:43], v[24:25], v[74:75]
	global_store_dwordx4 v[80:81], v[18:21], off offset:1024
	v_pk_mul_f32 v[24:25], v[192:193], v[84:85]
	s_nop 0
	v_pk_mul_f32 v[18:19], v[22:23], v[86:87]
	s_waitcnt vmcnt(8)
	v_pk_fma_f32 v[20:21], v[40:41], v[18:19], v[72:73]
	v_pk_fma_f32 v[18:19], v[38:39], v[24:25], v[70:71]
	global_store_dwordx4 v[80:81], v[18:21], off offset:2048
	s_nop 1
	v_pk_mul_f32 v[18:19], v[22:23], v[82:83]
	v_pk_mul_f32 v[22:23], v[192:193], v[78:79]
	s_waitcnt vmcnt(8)
	v_pk_fma_f32 v[20:21], v[36:37], v[18:19], v[68:69]
	v_pk_fma_f32 v[18:19], v[34:35], v[22:23], v[66:67]
	global_store_dwordx4 v[80:81], v[18:21], off offset:3072
.LBB0_1773:
	v_cvt_f32_i32_e32 v17, v17
	v_cvt_f32_i32_e32 v15, v15
	v_cvt_f32_i32_e32 v14, v14
	v_cvt_f32_i32_e32 v16, v16
	s_waitcnt lgkmcnt(0)
	v_lshlrev_b64 v[18:19], 12, v[188:189]
	v_lshl_add_u64 v[32:33], v[18:19], 0, v[190:191]
	v_cvt_f32_i32_e32 v29, v11
	v_cvt_f32_i32_e32 v28, v10
	v_cvt_f32_i32_e32 v31, v13
	v_cvt_f32_i32_e32 v30, v12
	v_cvt_f32_i32_e32 v25, v7
	v_cvt_f32_i32_e32 v24, v6
	v_cvt_f32_i32_e32 v27, v9
	v_cvt_f32_i32_e32 v26, v8
	v_cvt_f32_i32_e32 v19, v3
	v_cvt_f32_i32_e32 v18, v2
	v_cvt_f32_i32_e32 v23, v5
	v_cvt_f32_i32_e32 v22, v4
	v_mov_b32_e32 v187, v186
	v_readlane_b32 s68, v254, 8
	v_pk_mul_f32 v[14:15], v[186:187], v[14:15] op_sel_hi:[0,1]
	v_pk_mul_f32 v[16:17], v[186:187], v[16:17] op_sel_hi:[0,1]
	v_readlane_b32 s74, v254, 14
	v_readlane_b32 s75, v254, 15
	s_waitcnt vmcnt(4)
	v_pk_fma_f32 v[16:17], v[64:65], v[16:17], v[60:61]
	v_pk_fma_f32 v[14:15], v[62:63], v[14:15], v[58:59]
	s_mov_b64 s[98:99], 0x7000
	v_lshl_add_u64 v[20:21], v[250:251], 0, s[98:99]
	s_and_b64 vcc, exec, s[8:9]
	v_readlane_b32 s69, v254, 9
	v_readlane_b32 s70, v254, 10
	v_readlane_b32 s71, v254, 11
	v_readlane_b32 s72, v254, 12
	v_readlane_b32 s73, v254, 13
	global_store_dwordx4 v[20:21], v[14:17], off
	s_cbranch_vccnz .LBB0_1790
	v_readlane_b32 s2, v254, 40
	v_lshlrev_b64 v[60:61], 1, v[32:33]
	v_readlane_b32 s3, v254, 41
	s_nop 0
	v_cvt_pk_bf16_f32 v2, v14, v15
	s_nop 0
	v_cvt_pk_bf16_f32 v3, v16, v17
	v_mov_b32_e32 v10, v186
	v_mov_b32_e32 v11, v186
	v_lshl_add_u64 v[4:5], s[2:3], 0, v[60:61]
	global_store_dwordx2 v[4:5], v[2:3], off
	v_mul_f32_e32 v2, v15, v15
	v_mul_f32_e32 v3, v17, v17
	v_fmac_f32_e32 v2, v14, v14
	v_fmac_f32_e32 v3, v16, v16
	v_add_f32_e32 v12, v2, v3
	v_pk_mul_f32 v[2:3], v[10:11], v[30:31]
	v_pk_mul_f32 v[6:7], v[186:187], v[28:29]
	s_waitcnt vmcnt(5)
	v_pk_fma_f32 v[4:5], v[44:45], v[2:3], v[56:57]
	v_pk_fma_f32 v[2:3], v[42:43], v[6:7], v[54:55]
	v_or_b32_e32 v8, 32, v60
	v_mov_b32_e32 v9, v61
	global_store_dwordx4 v[20:21], v[2:5], off offset:1024
	s_nop 0
	v_cvt_pk_bf16_f32 v6, v2, v3
	s_nop 0
	v_cvt_pk_bf16_f32 v7, v4, v5
	v_lshl_add_u64 v[8:9], s[2:3], 0, v[8:9]
	global_store_dwordx2 v[8:9], v[6:7], off
	v_mul_f32_e32 v6, v3, v3
	v_mul_f32_e32 v7, v5, v5
	v_fmac_f32_e32 v6, v2, v2
	v_fmac_f32_e32 v7, v4, v4
	v_add_f32_e32 v6, v6, v7
	v_add_f32_e32 v32, v12, v6
	v_pk_mul_f32 v[6:7], v[10:11], v[26:27]
	v_pk_mul_f32 v[12:13], v[186:187], v[24:25]
	s_waitcnt vmcnt(6)
	v_pk_fma_f32 v[8:9], v[40:41], v[6:7], v[52:53]
	v_pk_fma_f32 v[6:7], v[38:39], v[12:13], v[50:51]
	v_mul_f32_e32 v13, v9, v9
	v_mul_f32_e32 v12, v7, v7
	v_fmac_f32_e32 v12, v6, v6
	v_fmac_f32_e32 v13, v8, v8
	v_add_f32_e32 v12, v12, v13
	v_add_f32_e32 v64, v32, v12
	v_pk_mul_f32 v[10:11], v[10:11], v[22:23]
	v_pk_mul_f32 v[32:33], v[186:187], v[18:19]
	s_waitcnt vmcnt(5)
	v_pk_fma_f32 v[12:13], v[36:37], v[10:11], v[48:49]
	v_pk_fma_f32 v[10:11], v[34:35], v[32:33], v[46:47]
	v_mul_f32_e32 v33, v13, v13
	v_mul_f32_e32 v32, v11, v11
	v_fmac_f32_e32 v32, v10, v10
	v_fmac_f32_e32 v33, v12, v12
	v_add_f32_e32 v32, v32, v33
	v_add_f32_e32 v33, v64, v32
	v_and_b32_e32 v64, 64, v236
	v_xor_b32_e32 v32, 16, v236
	v_add_u32_e32 v64, 64, v64
	v_cmp_lt_i32_e32 vcc, v32, v64
	v_or_b32_e32 v62, 0x100, v60
	v_mov_b32_e32 v63, v61
	v_cndmask_b32_e32 v32, v236, v32, vcc
	v_lshlrev_b32_e32 v32, 2, v32
	ds_bpermute_b32 v65, v32, v33
	global_store_dwordx4 v[20:21], v[6:9], off offset:2048
	s_nop 0
	v_cvt_pk_bf16_f32 v58, v6, v7
	s_nop 0
	v_cvt_pk_bf16_f32 v59, v8, v9
	v_lshl_add_u64 v[62:63], s[2:3], 0, v[62:63]
	global_store_dwordx2 v[62:63], v[58:59], off
	global_store_dwordx4 v[20:21], v[10:13], off offset:3072
	s_waitcnt lgkmcnt(0)
	v_add_f32_e32 v58, v33, v65
	v_xor_b32_e32 v33, 32, v236
	v_cmp_lt_i32_e32 vcc, v33, v64
	v_or_b32_e32 v60, 0x120, v60
	v_lshl_add_u64 v[60:61], s[2:3], 0, v[60:61]
	v_cndmask_b32_e32 v33, v236, v33, vcc
	v_lshlrev_b32_e32 v33, 2, v33
	ds_bpermute_b32 v59, v33, v58
	s_nop 0
	v_cvt_pk_bf16_f32 v62, v10, v11
	s_nop 0
	v_cvt_pk_bf16_f32 v63, v12, v13
	global_store_dwordx2 v[60:61], v[62:63], off
	s_and_saveexec_b64 s[2:3], s[6:7]
	s_cbranch_execz .LBB0_1776
	v_lshl_add_u64 v[60:61], v[188:189], 2, s[10:11]
	s_waitcnt lgkmcnt(0)
	v_add_f32_e32 v58, v58, v59
	global_atomic_add_f32 v[60:61], v58, off

; __device__ __forceinline__ f32x4 sig4(const f32x4 v) { return (f32x4){sigmoidf_(v[0]), sigmoidf_(v[1]), sigmoidf_(v[2]), sigmoidf_(v[3])}; }
;     __device__ __forceinline__ void operator()(const typename AccT<I8>::type (&acc)[2][2][4][2], const Unit& u, int wr, int wc, int fr, int fq) const {
;     ...
;                     for (int n = 0; n < 2; ++n) { const size_t o = off + bj * HALF + n * 16; const f32x4 b = cur.b[bj][n]; f32x4 v;
;                         if constexpr (I8) v = __builtin_convertvector(acc[ai][bj][m][n], f32x4) * rs * sv[bj][n]; else v = acc[ai][bj][m][n];
;                         if (MODE == 1) { const u32x2 pw = cur.pw[bj][n]; const f32x4 pp = (f32x4){bf_lo(pw.x), bf_hi(pw.x), bf_lo(pw.y), bf_hi(pw.y)}; v = sig4(I8 ? v : v * rs) * pp; }
;                         const f32x4 x = b + v; *(f32x4*)(out + o) = x;
.LBB0_1779:
	v_mov_b32_e32 v6, v186
	v_mov_b32_e32 v7, v186
	s_waitcnt lgkmcnt(0)
	v_pk_mul_f32 v[2:3], v[6:7], v[30:31]
	v_pk_mul_f32 v[8:9], v[186:187], v[28:29]
	s_waitcnt vmcnt(4)
	v_pk_fma_f32 v[4:5], v[44:45], v[2:3], v[56:57]
	v_pk_fma_f32 v[2:3], v[42:43], v[8:9], v[54:55]
	global_store_dwordx4 v[20:21], v[2:5], off offset:1024
	v_pk_mul_f32 v[8:9], v[186:187], v[24:25]
	s_nop 0
	v_pk_mul_f32 v[2:3], v[6:7], v[26:27]
	s_waitcnt vmcnt(4)
	v_pk_fma_f32 v[4:5], v[40:41], v[2:3], v[52:53]
	v_pk_fma_f32 v[2:3], v[38:39], v[8:9], v[50:51]
	global_store_dwordx4 v[20:21], v[2:5], off offset:2048
	s_nop 1
	v_pk_mul_f32 v[2:3], v[6:7], v[22:23]
	v_pk_mul_f32 v[6:7], v[186:187], v[18:19]
	s_waitcnt vmcnt(4)
	v_pk_fma_f32 v[4:5], v[36:37], v[2:3], v[48:49]
	v_pk_fma_f32 v[2:3], v[34:35], v[6:7], v[46:47]
	global_store_dwordx4 v[20:21], v[2:5], off offset:3072

;     __device__ __forceinline__ void load_row(RowIn& R, size_t off) const {
; #pragma unroll
;         for (int bj = 0; bj < 2; ++bj)
; #pragma unroll
;             for (int n = 0; n < 2; ++n) { const size_t o = off + bj * HALF + n * 16; R.b[bj][n] = *(const f32x4*)(res + o); if (MODE == 1) R.pw[bj][n] = *(const u32x2*)(PP + o); }
;     }
;     __device__ __forceinline__ void operator()(const typename AccT<I8>::type (&acc)[2][2][4][2], const Unit& u, int wr, int wc, int fr, int fq) const {
;         const int row0 = u.pm * BM + wr * 64 + fr, col0 = u.pn * BM + wc * 32 + 4 * fq;
;         f32x4 sv[2][2];
;         if (I8) {
; #pragma unroll
;             for (int bj = 0; bj < 2; ++bj)
; #pragma unroll
;                 for (int n = 0; n < 2; ++n) sv[bj][n] = *(const f32x4*)(swc + col0 + bj * HALF + n * 16);
;         }
;         float rsv[8];
; #pragma unroll
;         for (int s = 0; s < 8; ++s) { const int r = row0 + (s >> 2) * HALF + (s & 3) * 16; float rs = 1.f; if (MODE == 1) rs = __builtin_amdgcn_rsqf(rstd[r] * (1.0f / 4096.0f) + 1e-6f); if (I8) rs *= sxr[r]; rsv[s] = rs; }
;         RowIn cur, nxt;
;         load_row(cur, (size_t)row0 * 4096 + col0);
; #pragma unroll
;         for (int s = 0; s < 8; ++s) { const int ai = s >> 2, m = s & 3; const int r = row0 + ai * HALF + m * 16; const size_t off = (size_t)r * 4096 + col0;
;                 if (s + 1 < 8) load_row(nxt, (size_t)(row0 + ((s + 1) >> 2) * HALF + ((s + 1) & 3) * 16) * 4096 + col0);
;                 const float rs = rsv[s];
;                 float ss = 0.f, mx = 0.f;
; #pragma unroll
;                 for (int bj = 0; bj < 2; ++bj)
; #pragma unroll
;                     for (int n = 0; n < 2; ++n) { const size_t o = off + bj * HALF + n * 16; const f32x4 b = cur.b[bj][n]; f32x4 v;
;                         if constexpr (I8) v = __builtin_convertvector(acc[ai][bj][m][n], f32x4) * rs * sv[bj][n]; else v = acc[ai][bj][m][n];
;                         if (MODE == 1) { const u32x2 pw = cur.pw[bj][n]; const f32x4 pp = (f32x4){bf_lo(pw.x), bf_hi(pw.x), bf_lo(pw.y), bf_hi(pw.y)}; v = sig4(I8 ? v : v * rs) * pp; }
;                         const f32x4 x = b + v; *(f32x4*)(out + o) = x;
;                         if (MODE == 0 && XB) { u32x2 w; w.x = cvt_pk_bf16(x[0], x[1]); w.y = cvt_pk_bf16(x[2], x[3]); *(u32x2*)(XB + o) = w; ss += (x[0] * x[0] + x[1] * x[1]) + (x[2] * x[2] + x[3] * x[3]);
.LBB0_2095:
	s_lshl_b32 s98, s6, 4
	s_add_i32 s98, s98, s2
	s_sub_i32 s99, s98, 888
	s_cmp_lt_u32 s98, 888
	s_cselect_b32 s98, s98, s99
	s_mov_b32 s99, 0x4200000
	s_cselect_b32 s99, 0x3f600000, s99
	s_lshl_b32 s98, s98, 18
	s_add_u32 s98, s98, s99
	v_and_b32_e32 v250, 63, v0
	v_lshlrev_b32_e32 v250, 4, v250
	v_lshrrev_b32_e32 v251, 6, v0
	v_lshl_add_u32 v250, v251, 15, v250
	v_add_u32_e32 v250, s98, v250
	v_mov_b32_e32 v251, 0
	v_lshl_add_u64 v[250:251], s[96:97], 0, v[250:251]
	v_mov_b32_e32 v130, v0
	v_readlane_b32 s52, v254, 8
	v_ashrrev_i32_e32 v131, 2, v130
	v_and_b32_e32 v131, 0xffffffc0, v131
	v_lshl_add_u32 v131, s6, 8, v131
	v_bfe_u32 v162, v130, 4, 2
	v_and_or_b32 v184, v130, 15, v131
	v_lshrrev_b32_e32 v130, 1, v130
	v_and_b32_e32 v130, 0x60, v130
	v_lshl_or_b32 v130, s2, 8, v130
	v_lshl_or_b32 v182, v162, 2, v130
	v_ashrrev_i32_e32 v185, 31, v184
	v_readlane_b32 s58, v254, 14
	v_readlane_b32 s59, v254, 15
	v_ashrrev_i32_e32 v183, 31, v182
	v_lshlrev_b64 v[130:131], 14, v[184:185]
	s_mov_b64 s[6:7], s[58:59]
	v_or_b32_e32 v188, 16, v184
	v_lshl_add_u64 v[130:131], s[6:7], 0, v[130:131]
	v_lshlrev_b64 v[132:133], 2, v[182:183]
	v_ashrrev_i32_e32 v189, 31, v188
	v_lshl_add_u64 v[190:191], v[130:131], 0, v[132:133]
	v_lshlrev_b64 v[130:131], 14, v[188:189]
	v_lshl_add_u64 v[130:131], s[6:7], 0, v[130:131]
	v_lshl_add_u64 v[186:187], v[130:131], 0, v[132:133]
	s_mov_b64 s[98:99], 0x0
	v_lshl_add_u64 v[252:253], v[250:251], 0, s[98:99]
	global_load_dwordx4 v[158:161], v[252:253], off
	global_load_dwordx4 v[154:157], v[252:253], off offset:1024
	global_load_dwordx4 v[150:153], v[252:253], off offset:2048
	global_load_dwordx4 v[146:149], v[252:253], off offset:3072
	s_mov_b64 s[98:99], 0x1000
	v_lshl_add_u64 v[252:253], v[250:251], 0, s[98:99]
	global_load_dwordx4 v[142:145], v[252:253], off
	global_load_dwordx4 v[138:141], v[252:253], off offset:1024
	global_load_dwordx4 v[134:137], v[252:253], off offset:2048
	global_load_dwordx4 v[130:133], v[252:253], off offset:3072
	v_cndmask_b32_e64 v163, 0, 1, s[18:19]
	v_cmp_ne_u32_e64 s[8:9], 1, v163
	s_andn2_b64 vcc, exec, s[18:19]
	v_cmp_eq_u32_e64 s[6:7], 0, v162
	v_readlane_b32 s53, v254, 9
	v_readlane_b32 s54, v254, 10
	v_readlane_b32 s55, v254, 11
	v_readlane_b32 s56, v254, 12
	v_readlane_b32 s57, v254, 13
	s_waitcnt vmcnt(0)
	v_pk_add_f32 v[168:169], v[128:129], v[160:161]
	v_pk_add_f32 v[166:167], v[126:127], v[158:159]
	v_pk_add_f32 v[162:163], v[122:123], v[154:155]
	v_pk_add_f32 v[158:159], v[118:119], v[150:151]
	v_pk_add_f32 v[126:127], v[114:115], v[146:147]
	global_store_dwordx4 v[190:191], v[166:169], off
	s_cbranch_vccnz .LBB0_2154
	v_lshlrev_b64 v[114:115], 12, v[184:185]
	v_lshl_add_u64 v[114:115], v[114:115], 0, v[182:183]
	v_readlane_b32 s2, v254, 40
	v_lshlrev_b64 v[122:123], 1, v[114:115]
	v_readlane_b32 s3, v254, 41
	s_nop 0
	v_cvt_pk_bf16_f32 v118, v166, v167
	s_nop 0
	v_cvt_pk_bf16_f32 v119, v168, v169
	v_pk_add_f32 v[164:165], v[124:125], v[156:157]
	v_pk_add_f32 v[160:161], v[120:121], v[152:153]
	v_lshl_add_u64 v[114:115], s[2:3], 0, v[122:123]
	global_store_dwordx2 v[114:115], v[118:119], off
	v_mul_f32_e32 v114, v167, v167
	v_mul_f32_e32 v115, v169, v169
	v_fmac_f32_e32 v114, v166, v166
	v_fmac_f32_e32 v115, v168, v168
	v_or_b32_e32 v118, 32, v122
	v_mov_b32_e32 v119, v123
	v_add_f32_e32 v128, v114, v115
	global_store_dwordx4 v[190:191], v[162:165], off offset:64
	s_nop 0
	v_cvt_pk_bf16_f32 v114, v162, v163
	s_nop 0
	v_cvt_pk_bf16_f32 v115, v164, v165
	v_lshl_add_u64 v[118:119], s[2:3], 0, v[118:119]
	global_store_dwordx2 v[118:119], v[114:115], off
	v_mul_f32_e32 v114, v163, v163
	v_mul_f32_e32 v115, v165, v165
	v_fmac_f32_e32 v114, v162, v162
	v_fmac_f32_e32 v115, v164, v164
	v_add_f32_e32 v114, v114, v115
	v_add_f32_e32 v114, v128, v114
	v_mul_f32_e32 v115, v159, v159
	v_mul_f32_e32 v128, v161, v161
	v_fmac_f32_e32 v115, v158, v158
	v_fmac_f32_e32 v128, v160, v160
	v_add_f32_e32 v115, v115, v128
	v_pk_add_f32 v[128:129], v[116:117], v[148:149]
	v_add_f32_e32 v114, v114, v115
	v_mul_f32_e32 v115, v127, v127
	v_mul_f32_e32 v150, v129, v129
	v_fmac_f32_e32 v115, v126, v126
	v_fmac_f32_e32 v150, v128, v128
	v_add_f32_e32 v115, v115, v150
	v_and_b32_e32 v150, 64, v195
	v_add_f32_e32 v115, v114, v115
	v_xor_b32_e32 v114, 16, v195
	v_add_u32_e32 v150, 64, v150
	v_cmp_lt_i32_e32 vcc, v114, v150
	v_or_b32_e32 v146, 0x100, v122
	v_mov_b32_e32 v147, v123
	v_cndmask_b32_e32 v114, v195, v114, vcc
	v_lshlrev_b32_e32 v114, 2, v114
	ds_bpermute_b32 v151, v114, v115
	global_store_dwordx4 v[190:191], v[158:161], off offset:512
	s_nop 0
	v_cvt_pk_bf16_f32 v118, v158, v159
	s_nop 0
	v_cvt_pk_bf16_f32 v119, v160, v161
	v_lshl_add_u64 v[146:147], s[2:3], 0, v[146:147]
	global_store_dwordx2 v[146:147], v[118:119], off
	global_store_dwordx4 v[190:191], v[126:129], off offset:576
	s_waitcnt lgkmcnt(0)
	v_add_f32_e32 v118, v115, v151
	v_xor_b32_e32 v115, 32, v195
	v_cmp_lt_i32_e32 vcc, v115, v150
	v_or_b32_e32 v122, 0x120, v122
	v_lshl_add_u64 v[122:123], s[2:3], 0, v[122:123]
	v_cndmask_b32_e32 v115, v195, v115, vcc
	v_lshlrev_b32_e32 v115, 2, v115
	ds_bpermute_b32 v119, v115, v118
	s_nop 0
	v_cvt_pk_bf16_f32 v146, v126, v127
	s_nop 0
	v_cvt_pk_bf16_f32 v147, v128, v129
	global_store_dwordx2 v[122:123], v[146:147], off
	s_and_saveexec_b64 s[2:3], s[6:7]
	s_cbranch_execz .LBB0_2098
	v_lshl_add_u64 v[122:123], v[184:185], 2, s[10:11]
	s_waitcnt lgkmcnt(0)
	v_add_f32_e32 v118, v118, v119
	global_atomic_add_f32 v[122:123], v118, off

; __device__ __forceinline__ unsigned cvt_pk_bf16(float lo, float hi) { unsigned r; asm volatile("s_nop 0\n\tv_cvt_pk_bf16_f32 %0, %1, %2" : "=v"(r) : "v"(lo), "v"(hi)); return r; }
;     __device__ __forceinline__ void load_row(RowIn& R, size_t off) const {
; #pragma unroll
;         for (int bj = 0; bj < 2; ++bj)
; #pragma unroll
;             for (int n = 0; n < 2; ++n) { const size_t o = off + bj * HALF + n * 16; R.b[bj][n] = *(const f32x4*)(res + o); if (MODE == 1) R.pw[bj][n] = *(const u32x2*)(PP + o); }
;     }
;     __device__ __forceinline__ void operator()(const typename AccT<I8>::type (&acc)[2][2][4][2], const Unit& u, int wr, int wc, int fr, int fq) const {
;     ...
;         for (int s = 0; s < 8; ++s) { const int ai = s >> 2, m = s & 3; const int r = row0 + ai * HALF + m * 16; const size_t off = (size_t)r * 4096 + col0;
;                 if (s + 1 < 8) load_row(nxt, (size_t)(row0 + ((s + 1) >> 2) * HALF + ((s + 1) & 3) * 16) * 4096 + col0);
;                 const float rs = rsv[s];
;                 float ss = 0.f, mx = 0.f;
; #pragma unroll
;                 for (int bj = 0; bj < 2; ++bj)
; #pragma unroll
;                     for (int n = 0; n < 2; ++n) { const size_t o = off + bj * HALF + n * 16; const f32x4 b = cur.b[bj][n]; f32x4 v;
;                         if constexpr (I8) v = __builtin_convertvector(acc[ai][bj][m][n], f32x4) * rs * sv[bj][n]; else v = acc[ai][bj][m][n];
;                         if (MODE == 1) { const u32x2 pw = cur.pw[bj][n]; const f32x4 pp = (f32x4){bf_lo(pw.x), bf_hi(pw.x), bf_lo(pw.y), bf_hi(pw.y)}; v = sig4(I8 ? v : v * rs) * pp; }
;                         const f32x4 x = b + v; *(f32x4*)(out + o) = x;
;                         if (MODE == 0 && XB) { u32x2 w; w.x = cvt_pk_bf16(x[0], x[1]); w.y = cvt_pk_bf16(x[2], x[3]); *(u32x2*)(XB + o) = w; ss += (x[0] * x[0] + x[1] * x[1]) + (x[2] * x[2] + x[3] * x[3]);
;                             if (RM) mx = fmaxf(fmaxf(mx, fmaxf(fabsf(x[0]), fabsf(x[1]))), fmaxf(fabsf(x[2]), fabsf(x[3]))); } }
;                 if (MODE == 0 && XB) { ss += __shfl_xor(ss, 16); ss += __shfl_xor(ss, 32); if (fq == 0) unsafeAtomicAdd(SS + r, ss);
;                     if (RM) { mx = fmaxf(mx, __shfl_xor(mx, 16)); mx = fmaxf(mx, __shfl_xor(mx, 32)); if (fq == 0) atomicMax(RM + r, __builtin_bit_cast(unsigned, mx)); } }
.LBB0_2102:
	v_or_b32_e32 v156, 32, v184
	v_ashrrev_i32_e32 v157, 31, v156
	v_readlane_b32 s52, v254, 8
	s_waitcnt lgkmcnt(0)
	v_lshlrev_b64 v[114:115], 14, v[156:157]
	v_readlane_b32 s58, v254, 14
	v_readlane_b32 s59, v254, 15
	v_pk_add_f32 v[152:153], v[112:113], v[144:145]
	v_pk_add_f32 v[150:151], v[110:111], v[142:143]
	v_lshl_add_u64 v[114:115], s[58:59], 0, v[114:115]
	v_lshl_add_u64 v[154:155], v[182:183], 2, v[114:115]
	s_mov_b64 s[98:99], 0x2000
	v_lshl_add_u64 v[252:253], v[250:251], 0, s[98:99]
	global_load_dwordx4 v[126:129], v[252:253], off
	global_load_dwordx4 v[122:125], v[252:253], off offset:1024
	global_load_dwordx4 v[118:121], v[252:253], off offset:2048
	global_load_dwordx4 v[114:117], v[252:253], off offset:3072
	s_and_b64 vcc, exec, s[8:9]
	v_pk_add_f32 v[146:147], v[106:107], v[138:139]
	v_pk_add_f32 v[142:143], v[102:103], v[134:135]
	v_pk_add_f32 v[110:111], v[98:99], v[130:131]
	v_readlane_b32 s53, v254, 9
	v_readlane_b32 s54, v254, 10
	v_readlane_b32 s55, v254, 11
	v_readlane_b32 s56, v254, 12
	v_readlane_b32 s57, v254, 13
	global_store_dwordx4 v[186:187], v[150:153], off
	s_cbranch_vccnz .LBB0_2155
	v_lshlrev_b64 v[98:99], 12, v[188:189]
	v_lshl_add_u64 v[98:99], v[98:99], 0, v[182:183]
	v_readlane_b32 s2, v254, 40
	v_lshlrev_b64 v[106:107], 1, v[98:99]
	v_readlane_b32 s3, v254, 41
	s_nop 0
	v_cvt_pk_bf16_f32 v102, v150, v151
	s_nop 0
	v_cvt_pk_bf16_f32 v103, v152, v153
	v_pk_add_f32 v[148:149], v[108:109], v[140:141]
	v_pk_add_f32 v[144:145], v[104:105], v[136:137]
	v_lshl_add_u64 v[98:99], s[2:3], 0, v[106:107]
	global_store_dwordx2 v[98:99], v[102:103], off
	v_mul_f32_e32 v98, v151, v151
	v_mul_f32_e32 v99, v153, v153
	v_fmac_f32_e32 v98, v150, v150
	v_fmac_f32_e32 v99, v152, v152
	v_or_b32_e32 v102, 32, v106
	v_mov_b32_e32 v103, v107
	v_add_f32_e32 v112, v98, v99
	global_store_dwordx4 v[186:187], v[146:149], off offset:64
	s_nop 0
	v_cvt_pk_bf16_f32 v98, v146, v147
	s_nop 0
	v_cvt_pk_bf16_f32 v99, v148, v149
	v_lshl_add_u64 v[102:103], s[2:3], 0, v[102:103]
	global_store_dwordx2 v[102:103], v[98:99], off
	v_mul_f32_e32 v98, v147, v147
	v_mul_f32_e32 v99, v149, v149
	v_fmac_f32_e32 v98, v146, v146
	v_fmac_f32_e32 v99, v148, v148
	v_add_f32_e32 v98, v98, v99
	v_add_f32_e32 v98, v112, v98
	v_mul_f32_e32 v99, v143, v143
	v_mul_f32_e32 v112, v145, v145
	v_fmac_f32_e32 v99, v142, v142
	v_fmac_f32_e32 v112, v144, v144
	v_add_f32_e32 v99, v99, v112
	v_pk_add_f32 v[112:113], v[100:101], v[132:133]
	v_add_f32_e32 v98, v98, v99
	v_mul_f32_e32 v99, v111, v111
	v_mul_f32_e32 v134, v113, v113
	v_fmac_f32_e32 v99, v110, v110
	v_fmac_f32_e32 v134, v112, v112
	v_add_f32_e32 v99, v99, v134
	v_and_b32_e32 v134, 64, v195
	v_add_f32_e32 v99, v98, v99
	v_xor_b32_e32 v98, 16, v195
	v_add_u32_e32 v134, 64, v134
	v_cmp_lt_i32_e32 vcc, v98, v134
	v_or_b32_e32 v130, 0x100, v106
	v_mov_b32_e32 v131, v107
	v_cndmask_b32_e32 v98, v195, v98, vcc
	v_lshlrev_b32_e32 v98, 2, v98
	ds_bpermute_b32 v135, v98, v99
	global_store_dwordx4 v[186:187], v[142:145], off offset:512
	s_nop 0
	v_cvt_pk_bf16_f32 v102, v142, v143
	s_nop 0
	v_cvt_pk_bf16_f32 v103, v144, v145
	v_lshl_add_u64 v[130:131], s[2:3], 0, v[130:131]
	global_store_dwordx2 v[130:131], v[102:103], off
	global_store_dwordx4 v[186:187], v[110:113], off offset:576
	s_waitcnt lgkmcnt(0)
	v_add_f32_e32 v102, v99, v135
	v_xor_b32_e32 v99, 32, v195
	v_cmp_lt_i32_e32 vcc, v99, v134
	v_or_b32_e32 v106, 0x120, v106
	v_lshl_add_u64 v[106:107], s[2:3], 0, v[106:107]
	v_cndmask_b32_e32 v99, v195, v99, vcc
	v_lshlrev_b32_e32 v99, 2, v99
	ds_bpermute_b32 v103, v99, v102
	s_nop 0
	v_cvt_pk_bf16_f32 v130, v110, v111
	s_nop 0
	v_cvt_pk_bf16_f32 v131, v112, v113
	global_store_dwordx2 v[106:107], v[130:131], off
	s_and_saveexec_b64 s[2:3], s[6:7]
	s_cbranch_execz .LBB0_2105
	v_lshl_add_u64 v[106:107], v[188:189], 2, s[10:11]
	s_waitcnt lgkmcnt(0)
	v_add_f32_e32 v102, v102, v103
	global_atomic_add_f32 v[106:107], v102, off

; __device__ __forceinline__ unsigned cvt_pk_bf16(float lo, float hi) { unsigned r; asm volatile("s_nop 0\n\tv_cvt_pk_bf16_f32 %0, %1, %2" : "=v"(r) : "v"(lo), "v"(hi)); return r; }
;     __device__ __forceinline__ void load_row(RowIn& R, size_t off) const {
; #pragma unroll
;         for (int bj = 0; bj < 2; ++bj)
; #pragma unroll
;             for (int n = 0; n < 2; ++n) { const size_t o = off + bj * HALF + n * 16; R.b[bj][n] = *(const f32x4*)(res + o); if (MODE == 1) R.pw[bj][n] = *(const u32x2*)(PP + o); }
;     }
;     __device__ __forceinline__ void operator()(const typename AccT<I8>::type (&acc)[2][2][4][2], const Unit& u, int wr, int wc, int fr, int fq) const {
;     ...
;         for (int s = 0; s < 8; ++s) { const int ai = s >> 2, m = s & 3; const int r = row0 + ai * HALF + m * 16; const size_t off = (size_t)r * 4096 + col0;
;                 if (s + 1 < 8) load_row(nxt, (size_t)(row0 + ((s + 1) >> 2) * HALF + ((s + 1) & 3) * 16) * 4096 + col0);
;                 const float rs = rsv[s];
;                 float ss = 0.f, mx = 0.f;
; #pragma unroll
;                 for (int bj = 0; bj < 2; ++bj)
; #pragma unroll
;                     for (int n = 0; n < 2; ++n) { const size_t o = off + bj * HALF + n * 16; const f32x4 b = cur.b[bj][n]; f32x4 v;
;                         if constexpr (I8) v = __builtin_convertvector(acc[ai][bj][m][n], f32x4) * rs * sv[bj][n]; else v = acc[ai][bj][m][n];
;                         if (MODE == 1) { const u32x2 pw = cur.pw[bj][n]; const f32x4 pp = (f32x4){bf_lo(pw.x), bf_hi(pw.x), bf_lo(pw.y), bf_hi(pw.y)}; v = sig4(I8 ? v : v * rs) * pp; }
;                         const f32x4 x = b + v; *(f32x4*)(out + o) = x;
;                         if (MODE == 0 && XB) { u32x2 w; w.x = cvt_pk_bf16(x[0], x[1]); w.y = cvt_pk_bf16(x[2], x[3]); *(u32x2*)(XB + o) = w; ss += (x[0] * x[0] + x[1] * x[1]) + (x[2] * x[2] + x[3] * x[3]);
;                             if (RM) mx = fmaxf(fmaxf(mx, fmaxf(fabsf(x[0]), fabsf(x[1]))), fmaxf(fabsf(x[2]), fabsf(x[3]))); } }
;                 if (MODE == 0 && XB) { ss += __shfl_xor(ss, 16); ss += __shfl_xor(ss, 32); if (fq == 0) unsafeAtomicAdd(SS + r, ss);
;                     if (RM) { mx = fmaxf(mx, __shfl_xor(mx, 16)); mx = fmaxf(mx, __shfl_xor(mx, 32)); if (fq == 0) atomicMax(RM + r, __builtin_bit_cast(unsigned, mx)); } }
.LBB0_2109:
	v_or_b32_e32 v140, 48, v184
	v_ashrrev_i32_e32 v141, 31, v140
	v_readlane_b32 s52, v254, 8
	s_waitcnt lgkmcnt(0)
	v_lshlrev_b64 v[98:99], 14, v[140:141]
	v_readlane_b32 s58, v254, 14
	v_readlane_b32 s59, v254, 15
	s_waitcnt vmcnt(4)
	v_pk_add_f32 v[136:137], v[96:97], v[128:129]
	v_pk_add_f32 v[134:135], v[94:95], v[126:127]
	v_lshl_add_u64 v[98:99], s[58:59], 0, v[98:99]
	v_lshl_add_u64 v[138:139], v[182:183], 2, v[98:99]
	s_mov_b64 s[98:99], 0x3000
	v_lshl_add_u64 v[252:253], v[250:251], 0, s[98:99]
	global_load_dwordx4 v[110:113], v[252:253], off
	global_load_dwordx4 v[106:109], v[252:253], off offset:1024
	global_load_dwordx4 v[102:105], v[252:253], off offset:2048
	global_load_dwordx4 v[98:101], v[252:253], off offset:3072
	s_and_b64 vcc, exec, s[8:9]
	s_waitcnt vmcnt(7)
	v_pk_add_f32 v[130:131], v[90:91], v[122:123]
	s_waitcnt vmcnt(6)
	v_pk_add_f32 v[126:127], v[86:87], v[118:119]
	s_waitcnt vmcnt(5)
	v_pk_add_f32 v[94:95], v[82:83], v[114:115]
	v_readlane_b32 s53, v254, 9
	v_readlane_b32 s54, v254, 10
	v_readlane_b32 s55, v254, 11
	v_readlane_b32 s56, v254, 12
	v_readlane_b32 s57, v254, 13
	global_store_dwordx4 v[154:155], v[134:137], off
	s_cbranch_vccnz .LBB0_2156
	v_lshlrev_b64 v[82:83], 12, v[156:157]
	v_lshl_add_u64 v[82:83], v[82:83], 0, v[182:183]
	v_readlane_b32 s2, v254, 40
	v_lshlrev_b64 v[90:91], 1, v[82:83]
	v_readlane_b32 s3, v254, 41
	s_nop 0
	v_cvt_pk_bf16_f32 v86, v134, v135
	s_nop 0
	v_cvt_pk_bf16_f32 v87, v136, v137
	v_pk_add_f32 v[132:133], v[92:93], v[124:125]
	v_pk_add_f32 v[128:129], v[88:89], v[120:121]
	v_lshl_add_u64 v[82:83], s[2:3], 0, v[90:91]
	global_store_dwordx2 v[82:83], v[86:87], off
	v_mul_f32_e32 v82, v135, v135
	v_mul_f32_e32 v83, v137, v137
	v_fmac_f32_e32 v82, v134, v134
	v_fmac_f32_e32 v83, v136, v136
	v_or_b32_e32 v86, 32, v90
	v_mov_b32_e32 v87, v91
	v_add_f32_e32 v96, v82, v83
	global_store_dwordx4 v[154:155], v[130:133], off offset:64
	s_nop 0
	v_cvt_pk_bf16_f32 v82, v130, v131
	s_nop 0
	v_cvt_pk_bf16_f32 v83, v132, v133
	v_lshl_add_u64 v[86:87], s[2:3], 0, v[86:87]
	global_store_dwordx2 v[86:87], v[82:83], off
	v_mul_f32_e32 v82, v131, v131
	v_mul_f32_e32 v83, v133, v133
	v_fmac_f32_e32 v82, v130, v130
	v_fmac_f32_e32 v83, v132, v132
	v_add_f32_e32 v82, v82, v83
	v_add_f32_e32 v82, v96, v82
	v_mul_f32_e32 v83, v127, v127
	v_mul_f32_e32 v96, v129, v129
	v_fmac_f32_e32 v83, v126, v126
	v_fmac_f32_e32 v96, v128, v128
	v_add_f32_e32 v83, v83, v96
	v_pk_add_f32 v[96:97], v[84:85], v[116:117]
	v_add_f32_e32 v82, v82, v83
	v_mul_f32_e32 v83, v95, v95
	v_mul_f32_e32 v118, v97, v97
	v_fmac_f32_e32 v83, v94, v94
	v_fmac_f32_e32 v118, v96, v96
	v_add_f32_e32 v83, v83, v118
	v_and_b32_e32 v118, 64, v195
	v_add_f32_e32 v83, v82, v83
	v_xor_b32_e32 v82, 16, v195
	v_add_u32_e32 v118, 64, v118
	v_cmp_lt_i32_e32 vcc, v82, v118
	v_or_b32_e32 v114, 0x100, v90
	v_mov_b32_e32 v115, v91
	v_cndmask_b32_e32 v82, v195, v82, vcc
	v_lshlrev_b32_e32 v82, 2, v82
	ds_bpermute_b32 v119, v82, v83
	global_store_dwordx4 v[154:155], v[126:129], off offset:512
	s_nop 0
	v_cvt_pk_bf16_f32 v86, v126, v127
	s_nop 0
	v_cvt_pk_bf16_f32 v87, v128, v129
	v_lshl_add_u64 v[114:115], s[2:3], 0, v[114:115]
	global_store_dwordx2 v[114:115], v[86:87], off
	global_store_dwordx4 v[154:155], v[94:97], off offset:576
	s_waitcnt lgkmcnt(0)
	v_add_f32_e32 v86, v83, v119
	v_xor_b32_e32 v83, 32, v195
	v_cmp_lt_i32_e32 vcc, v83, v118
	v_or_b32_e32 v90, 0x120, v90
	v_lshl_add_u64 v[90:91], s[2:3], 0, v[90:91]
	v_cndmask_b32_e32 v83, v195, v83, vcc
	v_lshlrev_b32_e32 v83, 2, v83
	ds_bpermute_b32 v87, v83, v86
	s_nop 0
	v_cvt_pk_bf16_f32 v114, v94, v95
	s_nop 0
	v_cvt_pk_bf16_f32 v115, v96, v97
	global_store_dwordx2 v[90:91], v[114:115], off
	s_and_saveexec_b64 s[2:3], s[6:7]
	s_cbranch_execz .LBB0_2112
	v_lshl_add_u64 v[90:91], v[156:157], 2, s[10:11]
	s_waitcnt lgkmcnt(0)
	v_add_f32_e32 v86, v86, v87
	global_atomic_add_f32 v[90:91], v86, off

; __device__ __forceinline__ unsigned cvt_pk_bf16(float lo, float hi) { unsigned r; asm volatile("s_nop 0\n\tv_cvt_pk_bf16_f32 %0, %1, %2" : "=v"(r) : "v"(lo), "v"(hi)); return r; }
;     __device__ __forceinline__ void load_row(RowIn& R, size_t off) const {
; #pragma unroll
;         for (int bj = 0; bj < 2; ++bj)
; #pragma unroll
;             for (int n = 0; n < 2; ++n) { const size_t o = off + bj * HALF + n * 16; R.b[bj][n] = *(const f32x4*)(res + o); if (MODE == 1) R.pw[bj][n] = *(const u32x2*)(PP + o); }
;     }
;     __device__ __forceinline__ void operator()(const typename AccT<I8>::type (&acc)[2][2][4][2], const Unit& u, int wr, int wc, int fr, int fq) const {
;     ...
;         for (int s = 0; s < 8; ++s) { const int ai = s >> 2, m = s & 3; const int r = row0 + ai * HALF + m * 16; const size_t off = (size_t)r * 4096 + col0;
;                 if (s + 1 < 8) load_row(nxt, (size_t)(row0 + ((s + 1) >> 2) * HALF + ((s + 1) & 3) * 16) * 4096 + col0);
;                 const float rs = rsv[s];
;                 float ss = 0.f, mx = 0.f;
; #pragma unroll
;                 for (int bj = 0; bj < 2; ++bj)
; #pragma unroll
;                     for (int n = 0; n < 2; ++n) { const size_t o = off + bj * HALF + n * 16; const f32x4 b = cur.b[bj][n]; f32x4 v;
;                         if constexpr (I8) v = __builtin_convertvector(acc[ai][bj][m][n], f32x4) * rs * sv[bj][n]; else v = acc[ai][bj][m][n];
;                         if (MODE == 1) { const u32x2 pw = cur.pw[bj][n]; const f32x4 pp = (f32x4){bf_lo(pw.x), bf_hi(pw.x), bf_lo(pw.y), bf_hi(pw.y)}; v = sig4(I8 ? v : v * rs) * pp; }
;                         const f32x4 x = b + v; *(f32x4*)(out + o) = x;
;                         if (MODE == 0 && XB) { u32x2 w; w.x = cvt_pk_bf16(x[0], x[1]); w.y = cvt_pk_bf16(x[2], x[3]); *(u32x2*)(XB + o) = w; ss += (x[0] * x[0] + x[1] * x[1]) + (x[2] * x[2] + x[3] * x[3]);
;                             if (RM) mx = fmaxf(fmaxf(mx, fmaxf(fabsf(x[0]), fabsf(x[1]))), fmaxf(fabsf(x[2]), fabsf(x[3]))); } }
;                 if (MODE == 0 && XB) { ss += __shfl_xor(ss, 16); ss += __shfl_xor(ss, 32); if (fq == 0) unsafeAtomicAdd(SS + r, ss);
;                     if (RM) { mx = fmaxf(mx, __shfl_xor(mx, 16)); mx = fmaxf(mx, __shfl_xor(mx, 32)); if (fq == 0) atomicMax(RM + r, __builtin_bit_cast(unsigned, mx)); } }
.LBB0_2116:
	v_add_u32_e32 v122, 0x80, v184
	v_ashrrev_i32_e32 v123, 31, v122
	v_readlane_b32 s52, v254, 8
	s_waitcnt lgkmcnt(0)
	v_lshlrev_b64 v[82:83], 14, v[122:123]
	v_readlane_b32 s58, v254, 14
	v_readlane_b32 s59, v254, 15
	s_waitcnt vmcnt(4)
	v_pk_add_f32 v[120:121], v[80:81], v[112:113]
	v_pk_add_f32 v[118:119], v[78:79], v[110:111]
	v_lshl_add_u64 v[82:83], s[58:59], 0, v[82:83]
	v_lshl_add_u64 v[124:125], v[182:183], 2, v[82:83]
	s_mov_b64 s[98:99], 0x4000
	v_lshl_add_u64 v[252:253], v[250:251], 0, s[98:99]
	global_load_dwordx4 v[94:97], v[252:253], off
	global_load_dwordx4 v[90:93], v[252:253], off offset:1024
	global_load_dwordx4 v[86:89], v[252:253], off offset:2048
	global_load_dwordx4 v[82:85], v[252:253], off offset:3072
	s_and_b64 vcc, exec, s[8:9]
	s_waitcnt vmcnt(7)
	v_pk_add_f32 v[114:115], v[74:75], v[106:107]
	s_waitcnt vmcnt(6)
	v_pk_add_f32 v[110:111], v[70:71], v[102:103]
	s_waitcnt vmcnt(5)
	v_pk_add_f32 v[78:79], v[66:67], v[98:99]
	v_readlane_b32 s53, v254, 9
	v_readlane_b32 s54, v254, 10
	v_readlane_b32 s55, v254, 11
	v_readlane_b32 s56, v254, 12
	v_readlane_b32 s57, v254, 13
	global_store_dwordx4 v[138:139], v[118:121], off
	s_cbranch_vccnz .LBB0_2157
	v_lshlrev_b64 v[66:67], 12, v[140:141]
	v_lshl_add_u64 v[66:67], v[66:67], 0, v[182:183]
	v_readlane_b32 s2, v254, 40
	v_lshlrev_b64 v[74:75], 1, v[66:67]
	v_readlane_b32 s3, v254, 41
	s_nop 0
	v_cvt_pk_bf16_f32 v70, v118, v119
	s_nop 0
	v_cvt_pk_bf16_f32 v71, v120, v121
	v_pk_add_f32 v[116:117], v[76:77], v[108:109]
	v_pk_add_f32 v[112:113], v[72:73], v[104:105]
	v_lshl_add_u64 v[66:67], s[2:3], 0, v[74:75]
	global_store_dwordx2 v[66:67], v[70:71], off
	v_mul_f32_e32 v66, v119, v119
	v_mul_f32_e32 v67, v121, v121
	v_fmac_f32_e32 v66, v118, v118
	v_fmac_f32_e32 v67, v120, v120
	v_or_b32_e32 v70, 32, v74
	v_mov_b32_e32 v71, v75
	v_add_f32_e32 v80, v66, v67
	global_store_dwordx4 v[138:139], v[114:117], off offset:64
	s_nop 0
	v_cvt_pk_bf16_f32 v66, v114, v115
	s_nop 0
	v_cvt_pk_bf16_f32 v67, v116, v117
	v_lshl_add_u64 v[70:71], s[2:3], 0, v[70:71]
	global_store_dwordx2 v[70:71], v[66:67], off
	v_mul_f32_e32 v66, v115, v115
	v_mul_f32_e32 v67, v117, v117
	v_fmac_f32_e32 v66, v114, v114
	v_fmac_f32_e32 v67, v116, v116
	v_add_f32_e32 v66, v66, v67
	v_add_f32_e32 v66, v80, v66
	v_mul_f32_e32 v67, v111, v111
	v_mul_f32_e32 v80, v113, v113
	v_fmac_f32_e32 v67, v110, v110
	v_fmac_f32_e32 v80, v112, v112
	v_add_f32_e32 v67, v67, v80
	v_pk_add_f32 v[80:81], v[68:69], v[100:101]
	v_add_f32_e32 v66, v66, v67
	v_mul_f32_e32 v67, v79, v79
	v_mul_f32_e32 v102, v81, v81
	v_fmac_f32_e32 v67, v78, v78
	v_fmac_f32_e32 v102, v80, v80
	v_add_f32_e32 v67, v67, v102
	v_and_b32_e32 v102, 64, v195
	v_add_f32_e32 v67, v66, v67
	v_xor_b32_e32 v66, 16, v195
	v_add_u32_e32 v102, 64, v102
	v_cmp_lt_i32_e32 vcc, v66, v102
	v_or_b32_e32 v98, 0x100, v74
	v_mov_b32_e32 v99, v75
	v_cndmask_b32_e32 v66, v195, v66, vcc
	v_lshlrev_b32_e32 v66, 2, v66
	ds_bpermute_b32 v103, v66, v67
	global_store_dwordx4 v[138:139], v[110:113], off offset:512
	s_nop 0
	v_cvt_pk_bf16_f32 v70, v110, v111
	s_nop 0
	v_cvt_pk_bf16_f32 v71, v112, v113
	v_lshl_add_u64 v[98:99], s[2:3], 0, v[98:99]
	global_store_dwordx2 v[98:99], v[70:71], off
	global_store_dwordx4 v[138:139], v[78:81], off offset:576
	s_waitcnt lgkmcnt(0)
	v_add_f32_e32 v70, v67, v103
	v_xor_b32_e32 v67, 32, v195
	v_cmp_lt_i32_e32 vcc, v67, v102
	v_or_b32_e32 v74, 0x120, v74
	v_lshl_add_u64 v[74:75], s[2:3], 0, v[74:75]
	v_cndmask_b32_e32 v67, v195, v67, vcc
	v_lshlrev_b32_e32 v67, 2, v67
	ds_bpermute_b32 v71, v67, v70
	s_nop 0
	v_cvt_pk_bf16_f32 v98, v78, v79
	s_nop 0
	v_cvt_pk_bf16_f32 v99, v80, v81
	global_store_dwordx2 v[74:75], v[98:99], off
	s_and_saveexec_b64 s[2:3], s[6:7]
	s_cbranch_execz .LBB0_2119
	v_lshl_add_u64 v[74:75], v[140:141], 2, s[10:11]
	s_waitcnt lgkmcnt(0)
	v_add_f32_e32 v70, v70, v71
	global_atomic_add_f32 v[74:75], v70, off

; __device__ __forceinline__ unsigned cvt_pk_bf16(float lo, float hi) { unsigned r; asm volatile("s_nop 0\n\tv_cvt_pk_bf16_f32 %0, %1, %2" : "=v"(r) : "v"(lo), "v"(hi)); return r; }
;     __device__ __forceinline__ void load_row(RowIn& R, size_t off) const {
; #pragma unroll
;         for (int bj = 0; bj < 2; ++bj)
; #pragma unroll
;             for (int n = 0; n < 2; ++n) { const size_t o = off + bj * HALF + n * 16; R.b[bj][n] = *(const f32x4*)(res + o); if (MODE == 1) R.pw[bj][n] = *(const u32x2*)(PP + o); }
;     }
;     __device__ __forceinline__ void operator()(const typename AccT<I8>::type (&acc)[2][2][4][2], const Unit& u, int wr, int wc, int fr, int fq) const {
;     ...
;         for (int s = 0; s < 8; ++s) { const int ai = s >> 2, m = s & 3; const int r = row0 + ai * HALF + m * 16; const size_t off = (size_t)r * 4096 + col0;
;                 if (s + 1 < 8) load_row(nxt, (size_t)(row0 + ((s + 1) >> 2) * HALF + ((s + 1) & 3) * 16) * 4096 + col0);
;                 const float rs = rsv[s];
;                 float ss = 0.f, mx = 0.f;
; #pragma unroll
;                 for (int bj = 0; bj < 2; ++bj)
; #pragma unroll
;                     for (int n = 0; n < 2; ++n) { const size_t o = off + bj * HALF + n * 16; const f32x4 b = cur.b[bj][n]; f32x4 v;
;                         if constexpr (I8) v = __builtin_convertvector(acc[ai][bj][m][n], f32x4) * rs * sv[bj][n]; else v = acc[ai][bj][m][n];
;                         if (MODE == 1) { const u32x2 pw = cur.pw[bj][n]; const f32x4 pp = (f32x4){bf_lo(pw.x), bf_hi(pw.x), bf_lo(pw.y), bf_hi(pw.y)}; v = sig4(I8 ? v : v * rs) * pp; }
;                         const f32x4 x = b + v; *(f32x4*)(out + o) = x;
;                         if (MODE == 0 && XB) { u32x2 w; w.x = cvt_pk_bf16(x[0], x[1]); w.y = cvt_pk_bf16(x[2], x[3]); *(u32x2*)(XB + o) = w; ss += (x[0] * x[0] + x[1] * x[1]) + (x[2] * x[2] + x[3] * x[3]);
;                             if (RM) mx = fmaxf(fmaxf(mx, fmaxf(fabsf(x[0]), fabsf(x[1]))), fmaxf(fabsf(x[2]), fabsf(x[3]))); } }
;                 if (MODE == 0 && XB) { ss += __shfl_xor(ss, 16); ss += __shfl_xor(ss, 32); if (fq == 0) unsafeAtomicAdd(SS + r, ss);
;                     if (RM) { mx = fmaxf(mx, __shfl_xor(mx, 16)); mx = fmaxf(mx, __shfl_xor(mx, 32)); if (fq == 0) atomicMax(RM + r, __builtin_bit_cast(unsigned, mx)); } }
.LBB0_2123:
	v_or_b32_e32 v108, 16, v122
	v_ashrrev_i32_e32 v109, 31, v108
	v_readlane_b32 s52, v254, 8
	s_waitcnt lgkmcnt(0)
	v_lshlrev_b64 v[66:67], 14, v[108:109]
	v_readlane_b32 s58, v254, 14
	v_readlane_b32 s59, v254, 15
	s_waitcnt vmcnt(4)
	v_pk_add_f32 v[104:105], v[64:65], v[96:97]
	v_pk_add_f32 v[102:103], v[62:63], v[94:95]
	v_lshl_add_u64 v[66:67], s[58:59], 0, v[66:67]
	v_lshl_add_u64 v[106:107], v[182:183], 2, v[66:67]
	s_mov_b64 s[98:99], 0x5000
	v_lshl_add_u64 v[252:253], v[250:251], 0, s[98:99]
	global_load_dwordx4 v[78:81], v[252:253], off
	global_load_dwordx4 v[74:77], v[252:253], off offset:1024
	global_load_dwordx4 v[70:73], v[252:253], off offset:2048
	global_load_dwordx4 v[66:69], v[252:253], off offset:3072
	s_and_b64 vcc, exec, s[8:9]
	s_waitcnt vmcnt(7)
	v_pk_add_f32 v[98:99], v[58:59], v[90:91]
	s_waitcnt vmcnt(6)
	v_pk_add_f32 v[94:95], v[54:55], v[86:87]
	s_waitcnt vmcnt(5)
	v_pk_add_f32 v[62:63], v[50:51], v[82:83]
	v_readlane_b32 s53, v254, 9
	v_readlane_b32 s54, v254, 10
	v_readlane_b32 s55, v254, 11
	v_readlane_b32 s56, v254, 12
	v_readlane_b32 s57, v254, 13
	global_store_dwordx4 v[124:125], v[102:105], off
	s_cbranch_vccnz .LBB0_2158
	v_lshlrev_b64 v[50:51], 12, v[122:123]
	v_lshl_add_u64 v[50:51], v[50:51], 0, v[182:183]
	v_readlane_b32 s2, v254, 40
	v_lshlrev_b64 v[58:59], 1, v[50:51]
	v_readlane_b32 s3, v254, 41
	s_nop 0
	v_cvt_pk_bf16_f32 v54, v102, v103
	s_nop 0
	v_cvt_pk_bf16_f32 v55, v104, v105
	v_pk_add_f32 v[100:101], v[60:61], v[92:93]
	v_pk_add_f32 v[96:97], v[56:57], v[88:89]
	v_lshl_add_u64 v[50:51], s[2:3], 0, v[58:59]
	global_store_dwordx2 v[50:51], v[54:55], off
	v_mul_f32_e32 v50, v103, v103
	v_mul_f32_e32 v51, v105, v105
	v_fmac_f32_e32 v50, v102, v102
	v_fmac_f32_e32 v51, v104, v104
	v_or_b32_e32 v54, 32, v58
	v_mov_b32_e32 v55, v59
	v_add_f32_e32 v64, v50, v51
	global_store_dwordx4 v[124:125], v[98:101], off offset:64
	s_nop 0
	v_cvt_pk_bf16_f32 v50, v98, v99
	s_nop 0
	v_cvt_pk_bf16_f32 v51, v100, v101
	v_lshl_add_u64 v[54:55], s[2:3], 0, v[54:55]
	global_store_dwordx2 v[54:55], v[50:51], off
	v_mul_f32_e32 v50, v99, v99
	v_mul_f32_e32 v51, v101, v101
	v_fmac_f32_e32 v50, v98, v98
	v_fmac_f32_e32 v51, v100, v100
	v_add_f32_e32 v50, v50, v51
	v_add_f32_e32 v50, v64, v50
	v_mul_f32_e32 v51, v95, v95
	v_mul_f32_e32 v64, v97, v97
	v_fmac_f32_e32 v51, v94, v94
	v_fmac_f32_e32 v64, v96, v96
	v_add_f32_e32 v51, v51, v64
	v_pk_add_f32 v[64:65], v[52:53], v[84:85]
	v_add_f32_e32 v50, v50, v51
	v_mul_f32_e32 v51, v63, v63
	v_mul_f32_e32 v86, v65, v65
	v_fmac_f32_e32 v51, v62, v62
	v_fmac_f32_e32 v86, v64, v64
	v_add_f32_e32 v51, v51, v86
	v_and_b32_e32 v86, 64, v195
	v_add_f32_e32 v51, v50, v51
	v_xor_b32_e32 v50, 16, v195
	v_add_u32_e32 v86, 64, v86
	v_cmp_lt_i32_e32 vcc, v50, v86
	v_or_b32_e32 v82, 0x100, v58
	v_mov_b32_e32 v83, v59
	v_cndmask_b32_e32 v50, v195, v50, vcc
	v_lshlrev_b32_e32 v50, 2, v50
	ds_bpermute_b32 v87, v50, v51
	global_store_dwordx4 v[124:125], v[94:97], off offset:512
	s_nop 0
	v_cvt_pk_bf16_f32 v54, v94, v95
	s_nop 0
	v_cvt_pk_bf16_f32 v55, v96, v97
	v_lshl_add_u64 v[82:83], s[2:3], 0, v[82:83]
	global_store_dwordx2 v[82:83], v[54:55], off
	global_store_dwordx4 v[124:125], v[62:65], off offset:576
	s_waitcnt lgkmcnt(0)
	v_add_f32_e32 v54, v51, v87
	v_xor_b32_e32 v51, 32, v195
	v_cmp_lt_i32_e32 vcc, v51, v86
	v_or_b32_e32 v58, 0x120, v58
	v_lshl_add_u64 v[58:59], s[2:3], 0, v[58:59]
	v_cndmask_b32_e32 v51, v195, v51, vcc
	v_lshlrev_b32_e32 v51, 2, v51
	ds_bpermute_b32 v55, v51, v54
	s_nop 0
	v_cvt_pk_bf16_f32 v82, v62, v63
	s_nop 0
	v_cvt_pk_bf16_f32 v83, v64, v65
	global_store_dwordx2 v[58:59], v[82:83], off
	s_and_saveexec_b64 s[2:3], s[6:7]
	s_cbranch_execz .LBB0_2126
	v_lshl_add_u64 v[58:59], v[122:123], 2, s[10:11]
	s_waitcnt lgkmcnt(0)
	v_add_f32_e32 v54, v54, v55
	global_atomic_add_f32 v[58:59], v54, off

; __device__ __forceinline__ unsigned cvt_pk_bf16(float lo, float hi) { unsigned r; asm volatile("s_nop 0\n\tv_cvt_pk_bf16_f32 %0, %1, %2" : "=v"(r) : "v"(lo), "v"(hi)); return r; }
;     __device__ __forceinline__ void load_row(RowIn& R, size_t off) const {
; #pragma unroll
;         for (int bj = 0; bj < 2; ++bj)
; #pragma unroll
;             for (int n = 0; n < 2; ++n) { const size_t o = off + bj * HALF + n * 16; R.b[bj][n] = *(const f32x4*)(res + o); if (MODE == 1) R.pw[bj][n] = *(const u32x2*)(PP + o); }
;     }
;     __device__ __forceinline__ void operator()(const typename AccT<I8>::type (&acc)[2][2][4][2], const Unit& u, int wr, int wc, int fr, int fq) const {
;     ...
;         for (int s = 0; s < 8; ++s) { const int ai = s >> 2, m = s & 3; const int r = row0 + ai * HALF + m * 16; const size_t off = (size_t)r * 4096 + col0;
;                 if (s + 1 < 8) load_row(nxt, (size_t)(row0 + ((s + 1) >> 2) * HALF + ((s + 1) & 3) * 16) * 4096 + col0);
;                 const float rs = rsv[s];
;                 float ss = 0.f, mx = 0.f;
; #pragma unroll
;                 for (int bj = 0; bj < 2; ++bj)
; #pragma unroll
;                     for (int n = 0; n < 2; ++n) { const size_t o = off + bj * HALF + n * 16; const f32x4 b = cur.b[bj][n]; f32x4 v;
;                         if constexpr (I8) v = __builtin_convertvector(acc[ai][bj][m][n], f32x4) * rs * sv[bj][n]; else v = acc[ai][bj][m][n];
;                         if (MODE == 1) { const u32x2 pw = cur.pw[bj][n]; const f32x4 pp = (f32x4){bf_lo(pw.x), bf_hi(pw.x), bf_lo(pw.y), bf_hi(pw.y)}; v = sig4(I8 ? v : v * rs) * pp; }
;                         const f32x4 x = b + v; *(f32x4*)(out + o) = x;
;                         if (MODE == 0 && XB) { u32x2 w; w.x = cvt_pk_bf16(x[0], x[1]); w.y = cvt_pk_bf16(x[2], x[3]); *(u32x2*)(XB + o) = w; ss += (x[0] * x[0] + x[1] * x[1]) + (x[2] * x[2] + x[3] * x[3]);
;                             if (RM) mx = fmaxf(fmaxf(mx, fmaxf(fabsf(x[0]), fabsf(x[1]))), fmaxf(fabsf(x[2]), fabsf(x[3]))); } }
;                 if (MODE == 0 && XB) { ss += __shfl_xor(ss, 16); ss += __shfl_xor(ss, 32); if (fq == 0) unsafeAtomicAdd(SS + r, ss);
;                     if (RM) { mx = fmaxf(mx, __shfl_xor(mx, 16)); mx = fmaxf(mx, __shfl_xor(mx, 32)); if (fq == 0) atomicMax(RM + r, __builtin_bit_cast(unsigned, mx)); } }
.LBB0_2130:
	v_or_b32_e32 v92, 32, v122
	v_ashrrev_i32_e32 v93, 31, v92
	v_readlane_b32 s52, v254, 8
	s_waitcnt lgkmcnt(0)
	v_lshlrev_b64 v[50:51], 14, v[92:93]
	v_readlane_b32 s58, v254, 14
	v_readlane_b32 s59, v254, 15
	s_waitcnt vmcnt(4)
	v_pk_add_f32 v[88:89], v[48:49], v[80:81]
	v_pk_add_f32 v[86:87], v[46:47], v[78:79]
	v_lshl_add_u64 v[50:51], s[58:59], 0, v[50:51]
	v_lshl_add_u64 v[90:91], v[182:183], 2, v[50:51]
	s_mov_b64 s[98:99], 0x6000
	v_lshl_add_u64 v[252:253], v[250:251], 0, s[98:99]
	global_load_dwordx4 v[62:65], v[252:253], off
	global_load_dwordx4 v[58:61], v[252:253], off offset:1024
	global_load_dwordx4 v[54:57], v[252:253], off offset:2048
	global_load_dwordx4 v[50:53], v[252:253], off offset:3072
	s_and_b64 vcc, exec, s[8:9]
	s_waitcnt vmcnt(7)
	v_pk_add_f32 v[82:83], v[42:43], v[74:75]
	s_waitcnt vmcnt(6)
	v_pk_add_f32 v[78:79], v[38:39], v[70:71]
	s_waitcnt vmcnt(5)
	v_pk_add_f32 v[46:47], v[34:35], v[66:67]
	v_readlane_b32 s53, v254, 9
	v_readlane_b32 s54, v254, 10
	v_readlane_b32 s55, v254, 11
	v_readlane_b32 s56, v254, 12
	v_readlane_b32 s57, v254, 13
	global_store_dwordx4 v[106:107], v[86:89], off
	s_cbranch_vccnz .LBB0_2159
	v_lshlrev_b64 v[34:35], 12, v[108:109]
	v_lshl_add_u64 v[34:35], v[34:35], 0, v[182:183]
	v_readlane_b32 s2, v254, 40
	v_lshlrev_b64 v[42:43], 1, v[34:35]
	v_readlane_b32 s3, v254, 41
	s_nop 0
	v_cvt_pk_bf16_f32 v38, v86, v87
	s_nop 0
	v_cvt_pk_bf16_f32 v39, v88, v89
	v_pk_add_f32 v[84:85], v[44:45], v[76:77]
	v_pk_add_f32 v[80:81], v[40:41], v[72:73]
	v_lshl_add_u64 v[34:35], s[2:3], 0, v[42:43]
	global_store_dwordx2 v[34:35], v[38:39], off
	v_mul_f32_e32 v34, v87, v87
	v_mul_f32_e32 v35, v89, v89
	v_fmac_f32_e32 v34, v86, v86
	v_fmac_f32_e32 v35, v88, v88
	v_or_b32_e32 v38, 32, v42
	v_mov_b32_e32 v39, v43
	v_add_f32_e32 v48, v34, v35
	global_store_dwordx4 v[106:107], v[82:85], off offset:64
	s_nop 0
	v_cvt_pk_bf16_f32 v34, v82, v83
	s_nop 0
	v_cvt_pk_bf16_f32 v35, v84, v85
	v_lshl_add_u64 v[38:39], s[2:3], 0, v[38:39]
	global_store_dwordx2 v[38:39], v[34:35], off
	v_mul_f32_e32 v34, v83, v83
	v_mul_f32_e32 v35, v85, v85
	v_fmac_f32_e32 v34, v82, v82
	v_fmac_f32_e32 v35, v84, v84
	v_add_f32_e32 v34, v34, v35
	v_add_f32_e32 v34, v48, v34
	v_mul_f32_e32 v35, v79, v79
	v_mul_f32_e32 v48, v81, v81
	v_fmac_f32_e32 v35, v78, v78
	v_fmac_f32_e32 v48, v80, v80
	v_add_f32_e32 v35, v35, v48
	v_pk_add_f32 v[48:49], v[36:37], v[68:69]
	v_add_f32_e32 v34, v34, v35
	v_mul_f32_e32 v35, v47, v47
	v_mul_f32_e32 v70, v49, v49
	v_fmac_f32_e32 v35, v46, v46
	v_fmac_f32_e32 v70, v48, v48
	v_add_f32_e32 v35, v35, v70
	v_and_b32_e32 v70, 64, v195
	v_add_f32_e32 v35, v34, v35
	v_xor_b32_e32 v34, 16, v195
	v_add_u32_e32 v70, 64, v70
	v_cmp_lt_i32_e32 vcc, v34, v70
	v_or_b32_e32 v66, 0x100, v42
	v_mov_b32_e32 v67, v43
	v_cndmask_b32_e32 v34, v195, v34, vcc
	v_lshlrev_b32_e32 v34, 2, v34
	ds_bpermute_b32 v71, v34, v35
	global_store_dwordx4 v[106:107], v[78:81], off offset:512
	s_nop 0
	v_cvt_pk_bf16_f32 v38, v78, v79
	s_nop 0
	v_cvt_pk_bf16_f32 v39, v80, v81
	v_lshl_add_u64 v[66:67], s[2:3], 0, v[66:67]
	global_store_dwordx2 v[66:67], v[38:39], off
	global_store_dwordx4 v[106:107], v[46:49], off offset:576
	s_waitcnt lgkmcnt(0)
	v_add_f32_e32 v38, v35, v71
	v_xor_b32_e32 v35, 32, v195
	v_cmp_lt_i32_e32 vcc, v35, v70
	v_or_b32_e32 v42, 0x120, v42
	v_lshl_add_u64 v[42:43], s[2:3], 0, v[42:43]
	v_cndmask_b32_e32 v35, v195, v35, vcc
	v_lshlrev_b32_e32 v35, 2, v35
	ds_bpermute_b32 v39, v35, v38
	s_nop 0
	v_cvt_pk_bf16_f32 v66, v46, v47
	s_nop 0
	v_cvt_pk_bf16_f32 v67, v48, v49
	global_store_dwordx2 v[42:43], v[66:67], off
	s_and_saveexec_b64 s[2:3], s[6:7]
	s_cbranch_execz .LBB0_2133
	v_lshl_add_u64 v[42:43], v[108:109], 2, s[10:11]
	s_waitcnt lgkmcnt(0)
	v_add_f32_e32 v38, v38, v39
	global_atomic_add_f32 v[42:43], v38, off

; __device__ __forceinline__ unsigned cvt_pk_bf16(float lo, float hi) { unsigned r; asm volatile("s_nop 0\n\tv_cvt_pk_bf16_f32 %0, %1, %2" : "=v"(r) : "v"(lo), "v"(hi)); return r; }
;     __device__ __forceinline__ void load_row(RowIn& R, size_t off) const {
; #pragma unroll
;         for (int bj = 0; bj < 2; ++bj)
; #pragma unroll
;             for (int n = 0; n < 2; ++n) { const size_t o = off + bj * HALF + n * 16; R.b[bj][n] = *(const f32x4*)(res + o); if (MODE == 1) R.pw[bj][n] = *(const u32x2*)(PP + o); }
;     }
;     __device__ __forceinline__ void operator()(const typename AccT<I8>::type (&acc)[2][2][4][2], const Unit& u, int wr, int wc, int fr, int fq) const {
;     ...
;         for (int s = 0; s < 8; ++s) { const int ai = s >> 2, m = s & 3; const int r = row0 + ai * HALF + m * 16; const size_t off = (size_t)r * 4096 + col0;
;                 if (s + 1 < 8) load_row(nxt, (size_t)(row0 + ((s + 1) >> 2) * HALF + ((s + 1) & 3) * 16) * 4096 + col0);
;                 const float rs = rsv[s];
;                 float ss = 0.f, mx = 0.f;
; #pragma unroll
;                 for (int bj = 0; bj < 2; ++bj)
; #pragma unroll
;                     for (int n = 0; n < 2; ++n) { const size_t o = off + bj * HALF + n * 16; const f32x4 b = cur.b[bj][n]; f32x4 v;
;                         if constexpr (I8) v = __builtin_convertvector(acc[ai][bj][m][n], f32x4) * rs * sv[bj][n]; else v = acc[ai][bj][m][n];
;                         if (MODE == 1) { const u32x2 pw = cur.pw[bj][n]; const f32x4 pp = (f32x4){bf_lo(pw.x), bf_hi(pw.x), bf_lo(pw.y), bf_hi(pw.y)}; v = sig4(I8 ? v : v * rs) * pp; }
;                         const f32x4 x = b + v; *(f32x4*)(out + o) = x;
;                         if (MODE == 0 && XB) { u32x2 w; w.x = cvt_pk_bf16(x[0], x[1]); w.y = cvt_pk_bf16(x[2], x[3]); *(u32x2*)(XB + o) = w; ss += (x[0] * x[0] + x[1] * x[1]) + (x[2] * x[2] + x[3] * x[3]);
;                             if (RM) mx = fmaxf(fmaxf(mx, fmaxf(fabsf(x[0]), fabsf(x[1]))), fmaxf(fabsf(x[2]), fabsf(x[3]))); } }
;                 if (MODE == 0 && XB) { ss += __shfl_xor(ss, 16); ss += __shfl_xor(ss, 32); if (fq == 0) unsafeAtomicAdd(SS + r, ss);
;                     if (RM) { mx = fmaxf(mx, __shfl_xor(mx, 16)); mx = fmaxf(mx, __shfl_xor(mx, 32)); if (fq == 0) atomicMax(RM + r, __builtin_bit_cast(unsigned, mx)); } }
.LBB0_2137:
	v_or_b32_e32 v76, 48, v122
	v_ashrrev_i32_e32 v77, 31, v76
	v_readlane_b32 s52, v254, 8
	s_waitcnt lgkmcnt(0)
	v_lshlrev_b64 v[34:35], 14, v[76:77]
	v_readlane_b32 s58, v254, 14
	v_readlane_b32 s59, v254, 15
	s_waitcnt vmcnt(4)
	v_pk_add_f32 v[72:73], v[32:33], v[64:65]
	v_pk_add_f32 v[70:71], v[30:31], v[62:63]
	v_lshl_add_u64 v[34:35], s[58:59], 0, v[34:35]
	v_lshl_add_u64 v[74:75], v[182:183], 2, v[34:35]
	s_mov_b64 s[98:99], 0x7000
	v_lshl_add_u64 v[252:253], v[250:251], 0, s[98:99]
	global_load_dwordx4 v[46:49], v[252:253], off
	global_load_dwordx4 v[42:45], v[252:253], off offset:1024
	global_load_dwordx4 v[38:41], v[252:253], off offset:2048
	global_load_dwordx4 v[34:37], v[252:253], off offset:3072
	s_and_b64 vcc, exec, s[8:9]
	s_waitcnt vmcnt(7)
	v_pk_add_f32 v[66:67], v[26:27], v[58:59]
	s_waitcnt vmcnt(6)
	v_pk_add_f32 v[62:63], v[18:19], v[54:55]
	s_waitcnt vmcnt(5)
	v_pk_add_f32 v[30:31], v[14:15], v[50:51]
	v_readlane_b32 s53, v254, 9
	v_readlane_b32 s54, v254, 10
	v_readlane_b32 s55, v254, 11
	v_readlane_b32 s56, v254, 12
	v_readlane_b32 s57, v254, 13
	global_store_dwordx4 v[90:91], v[70:73], off
	s_cbranch_vccnz .LBB0_2160
	v_lshlrev_b64 v[14:15], 12, v[92:93]
	v_lshl_add_u64 v[14:15], v[14:15], 0, v[182:183]
	v_readlane_b32 s2, v254, 40
	v_lshlrev_b64 v[26:27], 1, v[14:15]
	v_readlane_b32 s3, v254, 41
	s_nop 0
	v_cvt_pk_bf16_f32 v18, v70, v71
	s_nop 0
	v_cvt_pk_bf16_f32 v19, v72, v73
	v_pk_add_f32 v[68:69], v[28:29], v[60:61]
	v_pk_add_f32 v[64:65], v[20:21], v[56:57]
	v_lshl_add_u64 v[14:15], s[2:3], 0, v[26:27]
	global_store_dwordx2 v[14:15], v[18:19], off
	v_mul_f32_e32 v14, v71, v71
	v_mul_f32_e32 v15, v73, v73
	v_fmac_f32_e32 v14, v70, v70
	v_fmac_f32_e32 v15, v72, v72
	v_or_b32_e32 v18, 32, v26
	v_mov_b32_e32 v19, v27
	v_add_f32_e32 v32, v14, v15
	global_store_dwordx4 v[90:91], v[66:69], off offset:64
	s_nop 0
	v_cvt_pk_bf16_f32 v14, v66, v67
	s_nop 0
	v_cvt_pk_bf16_f32 v15, v68, v69
	v_lshl_add_u64 v[18:19], s[2:3], 0, v[18:19]
	global_store_dwordx2 v[18:19], v[14:15], off
	v_mul_f32_e32 v14, v67, v67
	v_mul_f32_e32 v15, v69, v69
	v_fmac_f32_e32 v14, v66, v66
	v_fmac_f32_e32 v15, v68, v68
	v_add_f32_e32 v14, v14, v15
	v_add_f32_e32 v14, v32, v14
	v_mul_f32_e32 v15, v63, v63
	v_mul_f32_e32 v32, v65, v65
	v_fmac_f32_e32 v15, v62, v62
	v_fmac_f32_e32 v32, v64, v64
	v_add_f32_e32 v15, v15, v32
	v_pk_add_f32 v[32:33], v[16:17], v[52:53]
	v_add_f32_e32 v14, v14, v15
	v_mul_f32_e32 v15, v31, v31
	v_mul_f32_e32 v54, v33, v33
	v_fmac_f32_e32 v15, v30, v30
	v_fmac_f32_e32 v54, v32, v32
	v_add_f32_e32 v15, v15, v54
	v_and_b32_e32 v54, 64, v195
	v_add_f32_e32 v15, v14, v15
	v_xor_b32_e32 v14, 16, v195
	v_add_u32_e32 v54, 64, v54
	v_cmp_lt_i32_e32 vcc, v14, v54
	v_or_b32_e32 v50, 0x100, v26
	v_mov_b32_e32 v51, v27
	v_cndmask_b32_e32 v14, v195, v14, vcc
	v_lshlrev_b32_e32 v14, 2, v14
	ds_bpermute_b32 v55, v14, v15
	global_store_dwordx4 v[90:91], v[62:65], off offset:512
	s_nop 0
	v_cvt_pk_bf16_f32 v18, v62, v63
	s_nop 0
	v_cvt_pk_bf16_f32 v19, v64, v65
	v_lshl_add_u64 v[50:51], s[2:3], 0, v[50:51]
	global_store_dwordx2 v[50:51], v[18:19], off
	global_store_dwordx4 v[90:91], v[30:33], off offset:576
	s_waitcnt lgkmcnt(0)
	v_add_f32_e32 v18, v15, v55
	v_xor_b32_e32 v15, 32, v195
	v_cmp_lt_i32_e32 vcc, v15, v54
	v_or_b32_e32 v26, 0x120, v26
	v_lshl_add_u64 v[26:27], s[2:3], 0, v[26:27]
	v_cndmask_b32_e32 v15, v195, v15, vcc
	v_lshlrev_b32_e32 v15, 2, v15
	ds_bpermute_b32 v19, v15, v18
	s_nop 0
	v_cvt_pk_bf16_f32 v50, v30, v31
	s_nop 0
	v_cvt_pk_bf16_f32 v51, v32, v33
	global_store_dwordx2 v[26:27], v[50:51], off
	s_and_saveexec_b64 s[2:3], s[6:7]
	s_cbranch_execz .LBB0_2140
	v_lshl_add_u64 v[26:27], v[92:93], 2, s[10:11]
	s_waitcnt lgkmcnt(0)
	v_add_f32_e32 v18, v18, v19
	global_atomic_add_f32 v[26:27], v18, off
